# weight-conversion tiles: both fp32 row loads of a tile in flight before one wait, tile store as global_store
# speedup vs baseline: 1.0059x; 1.0059x over previous
; DI unsigned pk_bf16(float lo, float hi) { unsigned r; asm("v_cvt_pk_bf16_f32 %0, %1, %2" : "=v"(r) : "v"(lo), "v"(hi)); return r; }
; DI void tr_tile(const float* src, int src_ld, int k0, int n0, int mode, bf16_t* dst, int dst_ld, int dst_koff, float* tile) {
;     ...
;             tile[kk * 65 + nn4] = v[0]; tile[kk * 65 + nn4 + 1] = v[1]; tile[kk * 65 + nn4 + 2] = v[2]; tile[kk * 65 + nn4 + 3] = v[3]; }
;     }
;     __syncthreads();
;     {   const int nn = tid >> 3, ks = (tid & 7) * 8;
;         float v[8];
; #pragma unroll
;         for (int j = 0; j < 8; ++j) v[j] = tile[(ks + j) * 65 + nn];
;         u32x4 o; o[0] = pk_bf16(v[0], v[1]); o[1] = pk_bf16(v[2], v[3]); o[2] = pk_bf16(v[4], v[5]); o[3] = pk_bf16(v[6], v[7]);
;         *(u32x4*)(dst + (size_t)(n0 + nn) * dst_ld + dst_koff + k0 + ks) = o;
;     }
;     __syncthreads();
.LBB0_188:
	s_or_b64 exec, exec, s[20:21]
	v_add_u32_e32 v6, 0x2080, v11
	v_ashrrev_i32_e32 v8, 3, v0
	v_lshlrev_b32_e32 v0, 3, v0
	s_waitcnt vmcnt(0)
	ds_write2_b32 v6, v2, v3 offset1:1
	v_add_u32_e32 v2, 0x2088, v11
	v_and_b32_e32 v0, 56, v0
	ds_write2_b32 v2, v4, v5 offset1:1
	v_lshlrev_b32_e32 v2, 2, v8
	v_mul_u32_u24_e32 v3, 0x104, v0
	v_add3_u32 v6, 0, v2, v3
	s_waitcnt lgkmcnt(0)
	s_barrier
	ds_read2_b32 v[2:3], v6 offset1:65
	ds_read2_b32 v[4:5], v6 offset0:130 offset1:195
	v_add_u32_e32 v6, 0x400, v6
	s_waitcnt lgkmcnt(1)
	v_cvt_pk_bf16_f32 v2, v2, v3
	s_waitcnt lgkmcnt(0)
	v_cvt_pk_bf16_f32 v3, v4, v5
	ds_read2_b32 v[4:5], v6 offset0:4 offset1:69
	ds_read2_b32 v[6:7], v6 offset0:134 offset1:199
	s_waitcnt lgkmcnt(1)
	v_cvt_pk_bf16_f32 v4, v4, v5
	s_waitcnt lgkmcnt(0)
	v_cvt_pk_bf16_f32 v5, v6, v7
	v_add_u32_e32 v6, s3, v8
	v_ashrrev_i32_e32 v7, 31, v6
	v_lshlrev_b64 v[6:7], 11, v[6:7]
	v_lshl_add_u64 v[6:7], s[18:19], 0, v[6:7]
	s_ashr_i32 s41, s40, 31
	v_lshl_add_u64 v[6:7], s[40:41], 1, v[6:7]
	v_lshlrev_b32_e32 v0, 1, v0
	v_lshl_add_u64 v[6:7], v[6:7], 0, v[0:1]
	global_store_dwordx4 v[6:7], v[2:5], off
	s_waitcnt lgkmcnt(0)
	s_barrier

; #define PIN(i) (((KargTbl)__builtin_amdgcn_kernarg_segment_ptr())[i])
; DI unsigned pk_bf16(float lo, float hi) { unsigned r; asm("v_cvt_pk_bf16_f32 %0, %1, %2" : "=v"(r) : "v"(lo), "v"(hi)); return r; }
; DI int otid() { int t = threadIdx.x; asm volatile("" : "+v"(t)); return t; }
; DI void tr_tile(const float* src, int src_ld, int k0, int n0, int mode, bf16_t* dst, int dst_ld, int dst_koff, float* tile) {
;     const int tid = otid();
;     {   const int nn4 = (tid & 15) * 4; const int np = n0 + nn4;
;         int col = np; bool valid = true;
;         if (mode == 1) valid = np < IN_DIM;
;         if (mode == 3) valid = false;
;         if (mode == 2) { const int pn = np >> 8, bj = (np >> 7) & 1, jj = np & 127; col = bj * DFF + pn * 128 + jj; }
; #pragma unroll
;         for (int i = 0; i < 2; ++i) { const int kk = (tid >> 4) + 32 * i;
;             f32x4 v = (f32x4){0.f, 0.f, 0.f, 0.f};
;             if (valid) v = __builtin_nontemporal_load((const f32x4*)(src + (size_t)(k0 + kk) * src_ld + col));
;             tile[kk * 65 + nn4] = v[0]; tile[kk * 65 + nn4 + 1] = v[1]; tile[kk * 65 + nn4 + 2] = v[2]; tile[kk * 65 + nn4 + 3] = v[3]; }
;     }
;     __syncthreads();
;     {   const int nn = tid >> 3, ks = (tid & 7) * 8;
;         float v[8];
; #pragma unroll
;         for (int j = 0; j < 8; ++j) v[j] = tile[(ks + j) * 65 + nn];
;         u32x4 o; o[0] = pk_bf16(v[0], v[1]); o[1] = pk_bf16(v[2], v[3]); o[2] = pk_bf16(v[4], v[5]); o[3] = pk_bf16(v[6], v[7]);
;         *(u32x4*)(dst + (size_t)(n0 + nn) * dst_ld + dst_koff + k0 + ks) = o;
;     }
;     __syncthreads();
; DI void phase_convert_weights(unsigned char* ws, int l, unsigned char* lds, int t_lo, int t_hi, int bid_off) {
;     ...
;         } else if (it < T5) { const int j = it - T4, nt = j / 16, kt = j % 16;
;             tr_tile(PIN(21) + (size_t)l * 1024 * UPN, UPN, kt * 64, nt * 64, 2, (bf16_t*)(ws + WS_WUP), 1024, 0, tile);
;         } else { const int j = it - T5, nt = j / 44, kt = j % 44;
;             tr_tile(PIN(24) + (size_t)l * DFF * 1024, 1024, kt * 64, nt * 64, 0, (bf16_t*)(ws + WS_WDN), DFF, 0, tile);
.LBB0_190:
	s_cmpk_gt_i32 s2, 0x4ff
	s_mov_b64 s[20:21], -1
	s_cbranch_scc0 .LBB0_220
	s_cmpk_gt_u32 s2, 0x57f
	s_cbranch_scc0 .LBB0_217
	s_cmpk_gt_u32 s2, 0x5bf
	s_cbranch_scc0 .LBB0_214
	s_cmpk_gt_u32 s2, 0x5ff
	s_cbranch_scc0 .LBB0_211
	s_cmpk_gt_u32 s2, 0x63f
	s_cbranch_scc0 .LBB0_208
	s_cmpk_gt_u32 s2, 0x67f
	s_cbranch_scc0 .LBB0_205
	s_cmpk_gt_u32 s2, 0x77f
	s_cbranch_scc0 .LBB0_202
	s_cmpk_gt_u32 s2, 0xcff
	s_cbranch_scc0 .LBB0_199
	s_add_i32 s3, s2, 0xf300
	s_and_b32 s4, s3, 0xffff
	s_mul_i32 s4, s4, 0xba2f
	s_lshr_b32 s20, s4, 21
	s_mul_i32 s4, s20, 44
	s_sub_i32 s3, s3, s4
	s_load_dwordx2 s[4:5], s[0:1], 0xc0
	v_mov_b32_e32 v10, v176
	s_lshl_b32 s3, s3, 6
	s_and_b32 s3, s3, 0xffc0
	v_lshlrev_b32_e32 v0, 2, v10
	s_lshl_b32 s20, s20, 6
	v_and_b32_e32 v0, 60, v0
	v_ashrrev_i32_e32 v11, 4, v10
	v_or_b32_e32 v2, s20, v0
	v_add_u32_e32 v8, s3, v11
	v_lshlrev_b32_e32 v12, 2, v0
	v_lshlrev_b32_e32 v0, 2, v2
	v_ashrrev_i32_e32 v9, 31, v8
	s_waitcnt lgkmcnt(0)
	v_lshl_add_u64 v[6:7], s[4:5], 0, v[0:1]
	v_lshlrev_b64 v[2:3], 12, v[8:9]
	v_lshl_add_u64 v[2:3], v[6:7], 0, v[2:3]
	global_load_dwordx4 v[2:5], v[2:3], off nt
	v_mul_lo_u32 v0, v11, s81
	v_add3_u32 v0, 0, v12, v0
	s_movk_i32 s4, 0x1600
	s_lshl_b32 s72, s3, 1
	v_add_u32_e32 v104, 32, v8
	v_ashrrev_i32_e32 v105, 31, v104
	v_lshlrev_b64 v[104:105], 12, v[104:105]
	v_lshl_add_u64 v[104:105], v[6:7], 0, v[104:105]
	global_load_dwordx4 v[100:103], v[104:105], off nt
	s_waitcnt vmcnt(0)
	ds_write2_b32 v0, v2, v3 offset1:1
	ds_write2_b32 v0, v4, v5 offset0:2 offset1:3
	v_add_u32_e32 v6, 0x2080, v0
	v_add_u32_e32 v0, 0x2088, v0
	ds_write2_b32 v6, v100, v101 offset1:1
	v_lshlrev_b32_e32 v2, 3, v10
	ds_write2_b32 v0, v102, v103 offset1:1
	v_ashrrev_i32_e32 v0, 3, v10
	v_and_b32_e32 v8, 56, v2
	v_lshlrev_b32_e32 v2, 2, v0
	v_mul_u32_u24_e32 v3, 0x104, v8
	v_add3_u32 v6, 0, v2, v3
	s_waitcnt lgkmcnt(0)
	s_barrier
	ds_read2_b32 v[2:3], v6 offset1:65
	ds_read2_b32 v[4:5], v6 offset0:130 offset1:195
	v_add_u32_e32 v6, 0x400, v6
	s_waitcnt lgkmcnt(1)
	v_cvt_pk_bf16_f32 v2, v2, v3
	s_waitcnt lgkmcnt(0)
	v_cvt_pk_bf16_f32 v3, v4, v5
	ds_read2_b32 v[4:5], v6 offset0:4 offset1:69
	ds_read2_b32 v[6:7], v6 offset0:134 offset1:199
	s_waitcnt lgkmcnt(1)
	v_cvt_pk_bf16_f32 v4, v4, v5
	s_waitcnt lgkmcnt(0)
	v_cvt_pk_bf16_f32 v5, v6, v7
	v_add_u32_e32 v0, s20, v0
	v_mov_b64_e32 v[6:7], s[6:7]
	v_mad_i64_i32 v[6:7], s[4:5], v0, s4, v[6:7]
	v_lshl_add_u64 v[6:7], v[6:7], 0, s[72:73]
	v_lshlrev_b32_e32 v0, 1, v8
	v_lshl_add_u64 v[6:7], v[6:7], 0, v[0:1]
	global_store_dwordx4 v[6:7], v[2:5], off
	s_waitcnt lgkmcnt(0)
	s_barrier
	s_mov_b64 s[20:21], 0
.LBB0_199:
	s_andn2_b64 vcc, exec, s[20:21]
	s_cbranch_vccnz .LBB0_201
	s_lshl_b32 s20, s2, 2
	s_and_b32 s21, s20, 0x3fc0
	s_addk_i32 s21, 0xe200
	s_load_dwordx2 s[4:5], s[0:1], 0xa8
	s_bfe_i32 s22, s2, 0x10005
	s_lshr_b32 s23, s21, 1
	v_mov_b32_e32 v8, v176
	s_and_b32 s22, s22, 0xb00
	s_and_b32 s23, s23, 0x7fffff80
	s_and_b32 s20, s20, 64
	v_lshlrev_b32_e32 v0, 2, v8
	s_add_i32 s23, s23, s22
	s_lshl_b32 s3, s2, 6
	v_and_b32_e32 v2, 60, v0
	s_or_b32 s20, s23, s20
	s_and_b32 s3, s3, 0x3c0
	v_or_b32_e32 v0, s20, v2
	v_ashrrev_i32_e32 v9, 4, v8
	s_waitcnt lgkmcnt(0)
	v_lshl_add_u64 v[6:7], v[0:1], 2, s[4:5]
	v_add_u32_e32 v0, s3, v9
	s_movk_i32 s20, 0x5800
	v_lshlrev_b32_e32 v10, 2, v2
	v_mad_i64_i32 v[2:3], s[4:5], v0, s20, v[6:7]
	global_load_dwordx4 v[2:5], v[2:3], off nt
	v_mul_lo_u32 v9, v9, s81
	v_add3_u32 v9, 0, v10, v9
	v_add_u32_e32 v0, 32, v0
	s_lshl_b32 s72, s3, 1
	v_mad_i64_i32 v[104:105], s[4:5], v0, s20, v[6:7]
	global_load_dwordx4 v[100:103], v[104:105], off nt
	s_waitcnt vmcnt(0)
	ds_write2_b32 v9, v2, v3 offset1:1
	ds_write2_b32 v9, v4, v5 offset0:2 offset1:3
	v_add_u32_e32 v0, 0x2080, v9
	ds_write2_b32 v0, v100, v101 offset1:1
	v_add_u32_e32 v0, 0x2088, v9
	v_lshlrev_b32_e32 v2, 3, v8
	ds_write2_b32 v0, v102, v103 offset1:1
	v_ashrrev_i32_e32 v0, 3, v8
	v_and_b32_e32 v8, 56, v2
	v_lshlrev_b32_e32 v2, 2, v0
	v_mul_u32_u24_e32 v3, 0x104, v8
	v_add3_u32 v6, 0, v2, v3
	s_waitcnt lgkmcnt(0)
	s_barrier
	ds_read2_b32 v[2:3], v6 offset1:65
	ds_read2_b32 v[4:5], v6 offset0:130 offset1:195
	v_add_u32_e32 v6, 0x400, v6
	s_waitcnt lgkmcnt(1)
	v_cvt_pk_bf16_f32 v2, v2, v3
	s_waitcnt lgkmcnt(0)
	v_cvt_pk_bf16_f32 v3, v4, v5
	ds_read2_b32 v[4:5], v6 offset0:4 offset1:69
	ds_read2_b32 v[6:7], v6 offset0:134 offset1:199
	s_waitcnt lgkmcnt(1)
	v_cvt_pk_bf16_f32 v4, v4, v5
	s_waitcnt lgkmcnt(0)
	v_cvt_pk_bf16_f32 v5, v6, v7
	v_add_u32_e32 v6, s21, v0
	v_ashrrev_i32_e32 v7, 31, v6
	v_lshlrev_b64 v[6:7], 11, v[6:7]
	v_lshl_add_u64 v[6:7], s[8:9], 0, v[6:7]
	v_lshl_add_u64 v[6:7], v[6:7], 0, s[72:73]
	v_lshlrev_b32_e32 v0, 1, v8
	v_lshl_add_u64 v[6:7], v[6:7], 0, v[0:1]
	global_store_dwordx4 v[6:7], v[2:5], off
	s_waitcnt lgkmcnt(0)
	s_barrier

; #define PIN(i) (((KargTbl)__builtin_amdgcn_kernarg_segment_ptr())[i])
; DI unsigned pk_bf16(float lo, float hi) { unsigned r; asm("v_cvt_pk_bf16_f32 %0, %1, %2" : "=v"(r) : "v"(lo), "v"(hi)); return r; }
; DI int otid() { int t = threadIdx.x; asm volatile("" : "+v"(t)); return t; }
; DI void tr_tile(const float* src, int src_ld, int k0, int n0, int mode, bf16_t* dst, int dst_ld, int dst_koff, float* tile) {
;     const int tid = otid();
;     {   const int nn4 = (tid & 15) * 4; const int np = n0 + nn4;
;         int col = np; bool valid = true;
;         if (mode == 1) valid = np < IN_DIM;
;         if (mode == 3) valid = false;
;         if (mode == 2) { const int pn = np >> 8, bj = (np >> 7) & 1, jj = np & 127; col = bj * DFF + pn * 128 + jj; }
; #pragma unroll
;         for (int i = 0; i < 2; ++i) { const int kk = (tid >> 4) + 32 * i;
;             f32x4 v = (f32x4){0.f, 0.f, 0.f, 0.f};
;             if (valid) v = __builtin_nontemporal_load((const f32x4*)(src + (size_t)(k0 + kk) * src_ld + col));
;             tile[kk * 65 + nn4] = v[0]; tile[kk * 65 + nn4 + 1] = v[1]; tile[kk * 65 + nn4 + 2] = v[2]; tile[kk * 65 + nn4 + 3] = v[3]; }
;     }
;     __syncthreads();
;     {   const int nn = tid >> 3, ks = (tid & 7) * 8;
;         float v[8];
; #pragma unroll
;         for (int j = 0; j < 8; ++j) v[j] = tile[(ks + j) * 65 + nn];
;         u32x4 o; o[0] = pk_bf16(v[0], v[1]); o[1] = pk_bf16(v[2], v[3]); o[2] = pk_bf16(v[4], v[5]); o[3] = pk_bf16(v[6], v[7]);
;         *(u32x4*)(dst + (size_t)(n0 + nn) * dst_ld + dst_koff + k0 + ks) = o;
;     }
;     __syncthreads();
; DI void phase_convert_weights(unsigned char* ws, int l, unsigned char* lds, int t_lo, int t_hi, int bid_off) {
;     ...
;         } else if (it < T4) { const int j = it - T3, nt = j / 16, kt = j % 16;
;             tr_tile(PIN(20) + (size_t)l * 1024 * 1024, 1024, kt * 64, nt * 64, 0, (bf16_t*)(ws + WS_WO), 1024, 0, tile);
.LBB0_202:
	s_andn2_b64 vcc, exec, s[20:21]
	s_cbranch_vccnz .LBB0_204
	s_load_dwordx2 s[4:5], s[0:1], 0xa0
	s_lshl_b32 s3, s2, 6
	s_lshl_b32 s20, s2, 2
	v_mov_b32_e32 v10, v176
	s_and_b32 s3, s3, 0x3c0
	s_and_b32 s20, s20, 0x1fc0
	s_addk_i32 s20, 0xe600
	v_lshlrev_b32_e32 v0, 2, v10
	v_ashrrev_i32_e32 v11, 4, v10
	v_and_b32_e32 v2, 60, v0
	v_add_u32_e32 v8, s3, v11
	v_or_b32_e32 v0, s20, v2
	v_ashrrev_i32_e32 v9, 31, v8
	v_lshlrev_b32_e32 v12, 2, v2
	s_waitcnt lgkmcnt(0)
	v_lshl_add_u64 v[6:7], v[0:1], 2, s[4:5]
	v_lshlrev_b64 v[2:3], 12, v[8:9]
	v_lshl_add_u64 v[2:3], v[6:7], 0, v[2:3]
	global_load_dwordx4 v[2:5], v[2:3], off nt
	v_mul_lo_u32 v0, v11, s81
	v_add3_u32 v0, 0, v12, v0
	s_lshl_b32 s72, s3, 1
	v_add_u32_e32 v104, 32, v8
	v_ashrrev_i32_e32 v105, 31, v104
	v_lshlrev_b64 v[104:105], 12, v[104:105]
	v_lshl_add_u64 v[104:105], v[6:7], 0, v[104:105]
	global_load_dwordx4 v[100:103], v[104:105], off nt
	s_waitcnt vmcnt(0)
	ds_write2_b32 v0, v2, v3 offset1:1
	ds_write2_b32 v0, v4, v5 offset0:2 offset1:3
	v_add_u32_e32 v6, 0x2080, v0
	v_add_u32_e32 v0, 0x2088, v0
	ds_write2_b32 v6, v100, v101 offset1:1
	v_lshlrev_b32_e32 v2, 3, v10
	ds_write2_b32 v0, v102, v103 offset1:1
	v_ashrrev_i32_e32 v0, 3, v10
	v_and_b32_e32 v8, 56, v2
	v_lshlrev_b32_e32 v2, 2, v0
	v_mul_u32_u24_e32 v3, 0x104, v8
	v_add3_u32 v6, 0, v2, v3
	s_waitcnt lgkmcnt(0)
	s_barrier
	ds_read2_b32 v[2:3], v6 offset1:65
	ds_read2_b32 v[4:5], v6 offset0:130 offset1:195
	v_add_u32_e32 v6, 0x400, v6
	s_waitcnt lgkmcnt(1)
	v_cvt_pk_bf16_f32 v2, v2, v3
	s_waitcnt lgkmcnt(0)
	v_cvt_pk_bf16_f32 v3, v4, v5
	ds_read2_b32 v[4:5], v6 offset0:4 offset1:69
	ds_read2_b32 v[6:7], v6 offset0:134 offset1:199
	s_waitcnt lgkmcnt(1)
	v_cvt_pk_bf16_f32 v4, v4, v5
	s_waitcnt lgkmcnt(0)
	v_cvt_pk_bf16_f32 v5, v6, v7
	v_add_u32_e32 v6, s20, v0
	v_ashrrev_i32_e32 v7, 31, v6
	v_lshlrev_b64 v[6:7], 11, v[6:7]
	v_lshl_add_u64 v[6:7], s[10:11], 0, v[6:7]
	v_lshl_add_u64 v[6:7], v[6:7], 0, s[72:73]
	v_lshlrev_b32_e32 v0, 1, v8
	v_lshl_add_u64 v[6:7], v[6:7], 0, v[0:1]
	global_store_dwordx4 v[6:7], v[2:5], off
	s_waitcnt lgkmcnt(0)
	s_barrier

; #define PIN(i) (((KargTbl)__builtin_amdgcn_kernarg_segment_ptr())[i])
; DI unsigned pk_bf16(float lo, float hi) { unsigned r; asm("v_cvt_pk_bf16_f32 %0, %1, %2" : "=v"(r) : "v"(lo), "v"(hi)); return r; }
; DI int otid() { int t = threadIdx.x; asm volatile("" : "+v"(t)); return t; }
; DI void tr_tile(const float* src, int src_ld, int k0, int n0, int mode, bf16_t* dst, int dst_ld, int dst_koff, float* tile) {
;     const int tid = otid();
;     {   const int nn4 = (tid & 15) * 4; const int np = n0 + nn4;
;         int col = np; bool valid = true;
;         if (mode == 1) valid = np < IN_DIM;
;         if (mode == 3) valid = false;
;         if (mode == 2) { const int pn = np >> 8, bj = (np >> 7) & 1, jj = np & 127; col = bj * DFF + pn * 128 + jj; }
; #pragma unroll
;         for (int i = 0; i < 2; ++i) { const int kk = (tid >> 4) + 32 * i;
;             f32x4 v = (f32x4){0.f, 0.f, 0.f, 0.f};
;             if (valid) v = __builtin_nontemporal_load((const f32x4*)(src + (size_t)(k0 + kk) * src_ld + col));
;             tile[kk * 65 + nn4] = v[0]; tile[kk * 65 + nn4 + 1] = v[1]; tile[kk * 65 + nn4 + 2] = v[2]; tile[kk * 65 + nn4 + 3] = v[3]; }
;     }
;     __syncthreads();
;     {   const int nn = tid >> 3, ks = (tid & 7) * 8;
;         float v[8];
; #pragma unroll
;         for (int j = 0; j < 8; ++j) v[j] = tile[(ks + j) * 65 + nn];
;         u32x4 o; o[0] = pk_bf16(v[0], v[1]); o[1] = pk_bf16(v[2], v[3]); o[2] = pk_bf16(v[4], v[5]); o[3] = pk_bf16(v[6], v[7]);
;         *(u32x4*)(dst + (size_t)(n0 + nn) * dst_ld + dst_koff + k0 + ks) = o;
;     }
;     __syncthreads();
; DI void phase_convert_weights(unsigned char* ws, int l, unsigned char* lds, int t_lo, int t_hi, int bid_off) {
;     ...
;         } else if (it < T3) { const int j = it - T2c, nt = j / 4, kt = j % 4;
;             tr_tile(PIN(19) + (size_t)l * 256 * 1024, 1024, kt * 64, nt * 64, 0, (bf16_t*)(ws + WS_WBR) + 2048 * 512, 512, 256, tile);
.LBB0_205:
	s_andn2_b64 vcc, exec, s[20:21]
	s_cbranch_vccnz .LBB0_207
	s_load_dwordx2 s[4:5], s[0:1], 0x98
	s_lshl_b32 s3, s2, 6
	s_lshl_b32 s20, s2, 4
	v_mov_b32_e32 v10, v176
	s_and_b32 s3, s3, 0xc0
	s_and_b32 s20, s20, 0x7fc0
	s_addk_i32 s20, 0x9c00
	v_lshlrev_b32_e32 v0, 2, v10
	v_ashrrev_i32_e32 v11, 4, v10
	v_and_b32_e32 v2, 60, v0
	v_add_u32_e32 v8, s3, v11
	v_or_b32_e32 v0, s20, v2
	v_ashrrev_i32_e32 v9, 31, v8
	v_lshlrev_b32_e32 v12, 2, v2
	s_waitcnt lgkmcnt(0)
	v_lshl_add_u64 v[6:7], v[0:1], 2, s[4:5]
	v_lshlrev_b64 v[2:3], 12, v[8:9]
	v_lshl_add_u64 v[2:3], v[6:7], 0, v[2:3]
	global_load_dwordx4 v[2:5], v[2:3], off nt
	v_mul_lo_u32 v0, v11, s81
	v_add3_u32 v0, 0, v12, v0
	s_lshl_b32 s72, s3, 1
	v_add_u32_e32 v104, 32, v8
	v_ashrrev_i32_e32 v105, 31, v104
	v_lshlrev_b64 v[104:105], 12, v[104:105]
	v_lshl_add_u64 v[104:105], v[6:7], 0, v[104:105]
	global_load_dwordx4 v[100:103], v[104:105], off nt
	s_waitcnt vmcnt(0)
	ds_write2_b32 v0, v2, v3 offset1:1
	ds_write2_b32 v0, v4, v5 offset0:2 offset1:3
	v_add_u32_e32 v6, 0x2080, v0
	v_add_u32_e32 v0, 0x2088, v0
	ds_write2_b32 v6, v100, v101 offset1:1
	v_lshlrev_b32_e32 v2, 3, v10
	ds_write2_b32 v0, v102, v103 offset1:1
	v_ashrrev_i32_e32 v0, 3, v10
	v_and_b32_e32 v8, 56, v2
	v_lshlrev_b32_e32 v2, 2, v0
	v_mul_u32_u24_e32 v3, 0x104, v8
	v_add3_u32 v6, 0, v2, v3
	s_waitcnt lgkmcnt(0)
	s_barrier
	ds_read2_b32 v[2:3], v6 offset1:65
	ds_read2_b32 v[4:5], v6 offset0:130 offset1:195
	v_add_u32_e32 v6, 0x400, v6
	s_waitcnt lgkmcnt(1)
	v_cvt_pk_bf16_f32 v2, v2, v3
	s_waitcnt lgkmcnt(0)
	v_cvt_pk_bf16_f32 v3, v4, v5
	ds_read2_b32 v[4:5], v6 offset0:4 offset1:69
	ds_read2_b32 v[6:7], v6 offset0:134 offset1:199
	s_waitcnt lgkmcnt(1)
	v_cvt_pk_bf16_f32 v4, v4, v5
	s_waitcnt lgkmcnt(0)
	v_cvt_pk_bf16_f32 v5, v6, v7
	v_add_u32_e32 v6, s20, v0
	v_ashrrev_i32_e32 v7, 31, v6
	v_lshlrev_b64 v[6:7], 10, v[6:7]
	v_lshl_add_u64 v[6:7], s[84:85], 0, v[6:7]
	v_lshl_add_u64 v[6:7], v[6:7], 0, s[72:73]
	v_lshlrev_b32_e32 v0, 1, v8
	v_lshl_add_u64 v[6:7], v[6:7], 0, v[0:1]
	v_add_co_u32_e32 v6, vcc, 0x1562000, v6
	s_nop 1
	v_addc_co_u32_e32 v7, vcc, 0, v7, vcc
	flat_store_dwordx4 v[6:7], v[2:5] offset:512
	s_waitcnt lgkmcnt(0)
	s_barrier

; #define PIN(i) (((KargTbl)__builtin_amdgcn_kernarg_segment_ptr())[i])
; DI unsigned pk_bf16(float lo, float hi) { unsigned r; asm("v_cvt_pk_bf16_f32 %0, %1, %2" : "=v"(r) : "v"(lo), "v"(hi)); return r; }
; DI int otid() { int t = threadIdx.x; asm volatile("" : "+v"(t)); return t; }
; DI void tr_tile(const float* src, int src_ld, int k0, int n0, int mode, bf16_t* dst, int dst_ld, int dst_koff, float* tile) {
;     const int tid = otid();
;     {   const int nn4 = (tid & 15) * 4; const int np = n0 + nn4;
;         int col = np; bool valid = true;
;         if (mode == 1) valid = np < IN_DIM;
;         if (mode == 3) valid = false;
;         if (mode == 2) { const int pn = np >> 8, bj = (np >> 7) & 1, jj = np & 127; col = bj * DFF + pn * 128 + jj; }
; #pragma unroll
;         for (int i = 0; i < 2; ++i) { const int kk = (tid >> 4) + 32 * i;
;             f32x4 v = (f32x4){0.f, 0.f, 0.f, 0.f};
;             if (valid) v = __builtin_nontemporal_load((const f32x4*)(src + (size_t)(k0 + kk) * src_ld + col));
;             tile[kk * 65 + nn4] = v[0]; tile[kk * 65 + nn4 + 1] = v[1]; tile[kk * 65 + nn4 + 2] = v[2]; tile[kk * 65 + nn4 + 3] = v[3]; }
;     }
;     __syncthreads();
;     {   const int nn = tid >> 3, ks = (tid & 7) * 8;
;         float v[8];
; #pragma unroll
;         for (int j = 0; j < 8; ++j) v[j] = tile[(ks + j) * 65 + nn];
;         u32x4 o; o[0] = pk_bf16(v[0], v[1]); o[1] = pk_bf16(v[2], v[3]); o[2] = pk_bf16(v[4], v[5]); o[3] = pk_bf16(v[6], v[7]);
;         *(u32x4*)(dst + (size_t)(n0 + nn) * dst_ld + dst_koff + k0 + ks) = o;
;     }
;     __syncthreads();
; DI void phase_convert_weights(unsigned char* ws, int l, unsigned char* lds, int t_lo, int t_hi, int bid_off) {
;     ...
;         } else if (it < T2c) { const int j = it - T2b, nt = j / 4, kt = j % 4;
;             tr_tile(PIN(19), 1024, kt * 64, nt * 64, 3, (bf16_t*)(ws + WS_WBR) + 2048 * 512, 512, 0, tile);
.LBB0_208:
	s_andn2_b64 vcc, exec, s[20:21]
	s_cbranch_vccnz .LBB0_210
	v_mov_b32_e32 v0, v176
	s_load_dwordx2 s[4:5], s[0:1], 0x98
	s_lshl_b32 s3, s2, 4
	v_ashrrev_i32_e32 v2, 4, v0
	v_lshlrev_b32_e32 v3, 4, v0
	v_and_b32_e32 v3, 0xf0, v3
	v_mul_lo_u32 v2, v2, s81
	v_add3_u32 v2, 0, v3, v2
	v_ashrrev_i32_e32 v8, 3, v0
	v_lshlrev_b32_e32 v0, 3, v0
	ds_write2_b32 v2, v1, v1 offset1:1
	ds_write2_b32 v2, v1, v1 offset0:2 offset1:3
	v_add_u32_e32 v3, 0x2080, v2
	v_add_u32_e32 v2, 0x2088, v2
	v_and_b32_e32 v0, 56, v0
	ds_write2_b32 v3, v1, v1 offset1:1
	ds_write2_b32 v2, v1, v1 offset1:1
	v_lshlrev_b32_e32 v2, 2, v8
	v_mul_u32_u24_e32 v3, 0x104, v0
	v_add3_u32 v6, 0, v2, v3
	s_and_b32 s3, s3, 0x7fc0
	s_waitcnt lgkmcnt(0)
	s_barrier
	ds_read2_b32 v[2:3], v6 offset1:65
	ds_read2_b32 v[4:5], v6 offset0:130 offset1:195
	v_add_u32_e32 v6, 0x400, v6
	s_addk_i32 s3, 0xa000
	s_waitcnt lgkmcnt(0)
	v_cvt_pk_bf16_f32 v2, v2, v3
	v_cvt_pk_bf16_f32 v3, v4, v5
	ds_read2_b32 v[4:5], v6 offset0:4 offset1:69
	ds_read2_b32 v[6:7], v6 offset0:134 offset1:199
	s_waitcnt lgkmcnt(0)
	v_cvt_pk_bf16_f32 v4, v4, v5
	v_cvt_pk_bf16_f32 v5, v6, v7
	v_add_u32_e32 v6, s3, v8
	v_ashrrev_i32_e32 v7, 31, v6
	v_lshlrev_b64 v[6:7], 10, v[6:7]
	s_lshl_b32 s3, s2, 7
	v_lshl_add_u64 v[6:7], s[12:13], 0, v[6:7]
	s_and_b32 s72, s3, 0x180
	v_lshl_add_u64 v[6:7], v[6:7], 0, s[72:73]
	v_lshlrev_b32_e32 v0, 1, v0
	v_lshl_add_u64 v[6:7], v[6:7], 0, v[0:1]
	global_store_dwordx4 v[6:7], v[2:5], off
	s_waitcnt lgkmcnt(0)
	s_barrier

; #define PIN(i) (((KargTbl)__builtin_amdgcn_kernarg_segment_ptr())[i])
; DI unsigned pk_bf16(float lo, float hi) { unsigned r; asm("v_cvt_pk_bf16_f32 %0, %1, %2" : "=v"(r) : "v"(lo), "v"(hi)); return r; }
; DI int otid() { int t = threadIdx.x; asm volatile("" : "+v"(t)); return t; }
; DI void tr_tile(const float* src, int src_ld, int k0, int n0, int mode, bf16_t* dst, int dst_ld, int dst_koff, float* tile) {
;     const int tid = otid();
;     {   const int nn4 = (tid & 15) * 4; const int np = n0 + nn4;
;         int col = np; bool valid = true;
;         if (mode == 1) valid = np < IN_DIM;
;         if (mode == 3) valid = false;
;         if (mode == 2) { const int pn = np >> 8, bj = (np >> 7) & 1, jj = np & 127; col = bj * DFF + pn * 128 + jj; }
; #pragma unroll
;         for (int i = 0; i < 2; ++i) { const int kk = (tid >> 4) + 32 * i;
;             f32x4 v = (f32x4){0.f, 0.f, 0.f, 0.f};
;             if (valid) v = __builtin_nontemporal_load((const f32x4*)(src + (size_t)(k0 + kk) * src_ld + col));
;             tile[kk * 65 + nn4] = v[0]; tile[kk * 65 + nn4 + 1] = v[1]; tile[kk * 65 + nn4 + 2] = v[2]; tile[kk * 65 + nn4 + 3] = v[3]; }
;     }
;     __syncthreads();
;     {   const int nn = tid >> 3, ks = (tid & 7) * 8;
;         float v[8];
; #pragma unroll
;         for (int j = 0; j < 8; ++j) v[j] = tile[(ks + j) * 65 + nn];
;         u32x4 o; o[0] = pk_bf16(v[0], v[1]); o[1] = pk_bf16(v[2], v[3]); o[2] = pk_bf16(v[4], v[5]); o[3] = pk_bf16(v[6], v[7]);
;         *(u32x4*)(dst + (size_t)(n0 + nn) * dst_ld + dst_koff + k0 + ks) = o;
;     }
;     __syncthreads();
; DI void phase_convert_weights(unsigned char* ws, int l, unsigned char* lds, int t_lo, int t_hi, int bid_off) {
;     ...
;         } else if (it < T2) { const int j = it - T1, nt = j / 4, kt = j % 4;
;             tr_tile(PIN(18) + (size_t)l * 256 * 1024, 1024, kt * 64, nt * 64, 0, (bf16_t*)(ws + WS_WBR) + 1024 * 512, 512, 0, tile);
.LBB0_214:
	s_andn2_b64 vcc, exec, s[20:21]
	s_cbranch_vccnz .LBB0_216
	s_load_dwordx2 s[4:5], s[0:1], 0x90
	s_lshl_b32 s3, s2, 6
	s_lshl_b32 s20, s2, 4
	v_mov_b32_e32 v10, v176
	s_and_b32 s3, s3, 0xc0
	s_and_b32 s20, s20, 0x7fc0
	s_addk_i32 s20, 0xa800
	v_lshlrev_b32_e32 v0, 2, v10
	v_ashrrev_i32_e32 v11, 4, v10
	v_and_b32_e32 v2, 60, v0
	v_add_u32_e32 v8, s3, v11
	v_or_b32_e32 v0, s20, v2
	v_ashrrev_i32_e32 v9, 31, v8
	v_lshlrev_b32_e32 v12, 2, v2
	s_waitcnt lgkmcnt(0)
	v_lshl_add_u64 v[6:7], v[0:1], 2, s[4:5]
	v_lshlrev_b64 v[2:3], 12, v[8:9]
	v_lshl_add_u64 v[2:3], v[6:7], 0, v[2:3]
	global_load_dwordx4 v[2:5], v[2:3], off nt
	v_mul_lo_u32 v0, v11, s81
	v_add3_u32 v0, 0, v12, v0
	s_lshl_b32 s72, s3, 1
	v_add_u32_e32 v104, 32, v8
	v_ashrrev_i32_e32 v105, 31, v104
	v_lshlrev_b64 v[104:105], 12, v[104:105]
	v_lshl_add_u64 v[104:105], v[6:7], 0, v[104:105]
	global_load_dwordx4 v[100:103], v[104:105], off nt
	s_waitcnt vmcnt(0)
	ds_write2_b32 v0, v2, v3 offset1:1
	ds_write2_b32 v0, v4, v5 offset0:2 offset1:3
	v_add_u32_e32 v6, 0x2080, v0
	v_add_u32_e32 v0, 0x2088, v0
	ds_write2_b32 v6, v100, v101 offset1:1
	v_lshlrev_b32_e32 v2, 3, v10
	ds_write2_b32 v0, v102, v103 offset1:1
	v_ashrrev_i32_e32 v0, 3, v10
	v_and_b32_e32 v8, 56, v2
	v_lshlrev_b32_e32 v2, 2, v0
	v_mul_u32_u24_e32 v3, 0x104, v8
	v_add3_u32 v6, 0, v2, v3
	s_waitcnt lgkmcnt(0)
	s_barrier
	ds_read2_b32 v[2:3], v6 offset1:65
	ds_read2_b32 v[4:5], v6 offset0:130 offset1:195
	v_add_u32_e32 v6, 0x400, v6
	s_waitcnt lgkmcnt(1)
	v_cvt_pk_bf16_f32 v2, v2, v3
	s_waitcnt lgkmcnt(0)
	v_cvt_pk_bf16_f32 v3, v4, v5
	ds_read2_b32 v[4:5], v6 offset0:4 offset1:69
	ds_read2_b32 v[6:7], v6 offset0:134 offset1:199
	s_waitcnt lgkmcnt(1)
	v_cvt_pk_bf16_f32 v4, v4, v5
	s_waitcnt lgkmcnt(0)
	v_cvt_pk_bf16_f32 v5, v6, v7
	v_add_u32_e32 v6, s20, v0
	v_ashrrev_i32_e32 v7, 31, v6
	v_lshlrev_b64 v[6:7], 10, v[6:7]
	v_lshl_add_u64 v[6:7], s[14:15], 0, v[6:7]
	v_lshl_add_u64 v[6:7], v[6:7], 0, s[72:73]
	v_lshlrev_b32_e32 v0, 1, v8
	v_lshl_add_u64 v[6:7], v[6:7], 0, v[0:1]
	global_store_dwordx4 v[6:7], v[2:5], off
	s_waitcnt lgkmcnt(0)
	s_barrier

; #define PIN(i) (((KargTbl)__builtin_amdgcn_kernarg_segment_ptr())[i])
; DI unsigned pk_bf16(float lo, float hi) { unsigned r; asm("v_cvt_pk_bf16_f32 %0, %1, %2" : "=v"(r) : "v"(lo), "v"(hi)); return r; }
; DI int otid() { int t = threadIdx.x; asm volatile("" : "+v"(t)); return t; }
; DI void tr_tile(const float* src, int src_ld, int k0, int n0, int mode, bf16_t* dst, int dst_ld, int dst_koff, float* tile) {
;     const int tid = otid();
;     {   const int nn4 = (tid & 15) * 4; const int np = n0 + nn4;
;         int col = np; bool valid = true;
;         if (mode == 1) valid = np < IN_DIM;
;         if (mode == 3) valid = false;
;         if (mode == 2) { const int pn = np >> 8, bj = (np >> 7) & 1, jj = np & 127; col = bj * DFF + pn * 128 + jj; }
; #pragma unroll
;         for (int i = 0; i < 2; ++i) { const int kk = (tid >> 4) + 32 * i;
;             f32x4 v = (f32x4){0.f, 0.f, 0.f, 0.f};
;             if (valid) v = __builtin_nontemporal_load((const f32x4*)(src + (size_t)(k0 + kk) * src_ld + col));
;             tile[kk * 65 + nn4] = v[0]; tile[kk * 65 + nn4 + 1] = v[1]; tile[kk * 65 + nn4 + 2] = v[2]; tile[kk * 65 + nn4 + 3] = v[3]; }
;     }
;     __syncthreads();
;     {   const int nn = tid >> 3, ks = (tid & 7) * 8;
;         float v[8];
; #pragma unroll
;         for (int j = 0; j < 8; ++j) v[j] = tile[(ks + j) * 65 + nn];
;         u32x4 o; o[0] = pk_bf16(v[0], v[1]); o[1] = pk_bf16(v[2], v[3]); o[2] = pk_bf16(v[4], v[5]); o[3] = pk_bf16(v[6], v[7]);
;         *(u32x4*)(dst + (size_t)(n0 + nn) * dst_ld + dst_koff + k0 + ks) = o;
;     }
;     __syncthreads();
; DI void phase_convert_weights(unsigned char* ws, int l, unsigned char* lds, int t_lo, int t_hi, int bid_off) {
;     ...
;         } else if (it < T1) { const int j = it - T0, nt = j / 8, kt = j % 8;
;             tr_tile(PIN(17) + (size_t)l * 512 * 1024, 1024, kt * 64, nt * 64, 0, (bf16_t*)(ws + WS_WBR), 512, 0, tile);
.LBB0_217:
	s_andn2_b64 vcc, exec, s[20:21]
	s_cbranch_vccnz .LBB0_219
	s_load_dwordx2 s[4:5], s[0:1], 0x88
	s_lshl_b32 s3, s2, 6
	s_lshl_b32 s20, s2, 3
	v_mov_b32_e32 v10, v176
	s_and_b32 s3, s3, 0x1c0
	s_and_b32 s20, s20, 0x3fc0
	s_addk_i32 s20, 0xd800
	v_lshlrev_b32_e32 v0, 2, v10
	v_ashrrev_i32_e32 v11, 4, v10
	v_and_b32_e32 v2, 60, v0
	v_add_u32_e32 v8, s3, v11
	v_or_b32_e32 v0, s20, v2
	v_ashrrev_i32_e32 v9, 31, v8
	v_lshlrev_b32_e32 v12, 2, v2
	s_waitcnt lgkmcnt(0)
	v_lshl_add_u64 v[6:7], v[0:1], 2, s[4:5]
	v_lshlrev_b64 v[2:3], 12, v[8:9]
	v_lshl_add_u64 v[2:3], v[6:7], 0, v[2:3]
	global_load_dwordx4 v[2:5], v[2:3], off nt
	v_mul_lo_u32 v0, v11, s81
	v_add3_u32 v0, 0, v12, v0
	s_lshl_b32 s72, s3, 1
	v_add_u32_e32 v104, 32, v8
	v_ashrrev_i32_e32 v105, 31, v104
	v_lshlrev_b64 v[104:105], 12, v[104:105]
	v_lshl_add_u64 v[104:105], v[6:7], 0, v[104:105]
	global_load_dwordx4 v[100:103], v[104:105], off nt
	s_waitcnt vmcnt(0)
	ds_write2_b32 v0, v2, v3 offset1:1
	ds_write2_b32 v0, v4, v5 offset0:2 offset1:3
	v_add_u32_e32 v6, 0x2080, v0
	v_add_u32_e32 v0, 0x2088, v0
	ds_write2_b32 v6, v100, v101 offset1:1
	v_lshlrev_b32_e32 v2, 3, v10
	ds_write2_b32 v0, v102, v103 offset1:1
	v_ashrrev_i32_e32 v0, 3, v10
	v_and_b32_e32 v8, 56, v2
	v_lshlrev_b32_e32 v2, 2, v0
	v_mul_u32_u24_e32 v3, 0x104, v8
	v_add3_u32 v6, 0, v2, v3
	s_waitcnt lgkmcnt(0)
	s_barrier
	ds_read2_b32 v[2:3], v6 offset1:65
	ds_read2_b32 v[4:5], v6 offset0:130 offset1:195
	v_add_u32_e32 v6, 0x400, v6
	s_waitcnt lgkmcnt(1)
	v_cvt_pk_bf16_f32 v2, v2, v3
	s_waitcnt lgkmcnt(0)
	v_cvt_pk_bf16_f32 v3, v4, v5
	ds_read2_b32 v[4:5], v6 offset0:4 offset1:69
	ds_read2_b32 v[6:7], v6 offset0:134 offset1:199
	s_waitcnt lgkmcnt(1)
	v_cvt_pk_bf16_f32 v4, v4, v5
	s_waitcnt lgkmcnt(0)
	v_cvt_pk_bf16_f32 v5, v6, v7
	v_add_u32_e32 v6, s20, v0
	v_ashrrev_i32_e32 v7, 31, v6
	v_lshlrev_b64 v[6:7], 10, v[6:7]
	v_lshl_add_u64 v[6:7], s[16:17], 0, v[6:7]
	v_lshl_add_u64 v[6:7], v[6:7], 0, s[72:73]
	v_lshlrev_b32_e32 v0, 1, v8
	v_lshl_add_u64 v[6:7], v[6:7], 0, v[0:1]
	global_store_dwordx4 v[6:7], v[2:5], off
	s_waitcnt lgkmcnt(0)
	s_barrier

; DI unsigned pk_bf16(float lo, float hi) { unsigned r; asm("v_cvt_pk_bf16_f32 %0, %1, %2" : "=v"(r) : "v"(lo), "v"(hi)); return r; }
; DI int obid() { int t = blockIdx.x; asm volatile("" : "+s"(t)); return t; }
; DI int ogrid() { int t = gridDim.x; asm volatile("" : "+s"(t)); return t; }
; DI void tr_tile(const float* src, int src_ld, int k0, int n0, int mode, bf16_t* dst, int dst_ld, int dst_koff, float* tile) {
;     ...
;             tile[kk * 65 + nn4] = v[0]; tile[kk * 65 + nn4 + 1] = v[1]; tile[kk * 65 + nn4 + 2] = v[2]; tile[kk * 65 + nn4 + 3] = v[3]; }
;     }
;     __syncthreads();
;     {   const int nn = tid >> 3, ks = (tid & 7) * 8;
;         float v[8];
; #pragma unroll
;         for (int j = 0; j < 8; ++j) v[j] = tile[(ks + j) * 65 + nn];
;         u32x4 o; o[0] = pk_bf16(v[0], v[1]); o[1] = pk_bf16(v[2], v[3]); o[2] = pk_bf16(v[4], v[5]); o[3] = pk_bf16(v[6], v[7]);
;         *(u32x4*)(dst + (size_t)(n0 + nn) * dst_ld + dst_koff + k0 + ks) = o;
;     }
;     __syncthreads();
; DI void phase_convert_weights(unsigned char* ws, int l, unsigned char* lds, int t_lo, int t_hi, int bid_off) {
;     ...
;     for (int it = t_lo + (obid() - bid_off); it < t_hi; it += ogrid() - bid_off) {
.LBB0_375:
	s_or_b64 exec, exec, s[8:9]
	v_add_u32_e32 v6, 0x2080, v11
	v_ashrrev_i32_e32 v8, 3, v0
	v_lshlrev_b32_e32 v0, 3, v0
	s_waitcnt vmcnt(0)
	ds_write2_b32 v6, v2, v3 offset1:1
	v_add_u32_e32 v2, 0x2088, v11
	v_and_b32_e32 v0, 56, v0
	ds_write2_b32 v2, v4, v5 offset1:1
	v_lshlrev_b32_e32 v2, 2, v8
	v_mul_u32_u24_e32 v3, 0x104, v0
	v_add3_u32 v6, 0, v2, v3
	s_waitcnt lgkmcnt(0)
	s_barrier
	ds_read2_b32 v[2:3], v6 offset1:65
	ds_read2_b32 v[4:5], v6 offset0:130 offset1:195
	v_add_u32_e32 v6, 0x400, v6
	s_waitcnt lgkmcnt(1)
	v_cvt_pk_bf16_f32 v2, v2, v3
	s_waitcnt lgkmcnt(0)
	v_cvt_pk_bf16_f32 v3, v4, v5
	ds_read2_b32 v[4:5], v6 offset0:4 offset1:69
	ds_read2_b32 v[6:7], v6 offset0:134 offset1:199
	s_waitcnt lgkmcnt(1)
	v_cvt_pk_bf16_f32 v4, v4, v5
	s_waitcnt lgkmcnt(0)
	v_cvt_pk_bf16_f32 v5, v6, v7
	v_add_u32_e32 v6, s7, v8
	v_ashrrev_i32_e32 v7, 31, v6
	v_lshlrev_b64 v[6:7], 11, v[6:7]
	v_lshl_add_u64 v[6:7], s[4:5], 0, v[6:7]
	s_ashr_i32 s7, s6, 31
	v_lshl_add_u64 v[6:7], s[6:7], 1, v[6:7]
	v_lshlrev_b32_e32 v0, 1, v0
	v_lshl_add_u64 v[6:7], v[6:7], 0, v[0:1]
	s_mov_b32 s6, s66
	s_sub_i32 s3, s3, s2
	global_store_dwordx4 v[6:7], v[2:5], off
	s_waitcnt lgkmcnt(0)
	s_barrier
	s_add_i32 s3, s6, s3
	s_cmpk_gt_i32 s3, 0x4ff
	s_cbranch_scc1 .LBB0_380

; DI unsigned pk_bf16(float lo, float hi) { unsigned r; asm("v_cvt_pk_bf16_f32 %0, %1, %2" : "=v"(r) : "v"(lo), "v"(hi)); return r; }
; DI void tr_tile(const float* src, int src_ld, int k0, int n0, int mode, bf16_t* dst, int dst_ld, int dst_koff, float* tile) {
;     ...
;             tile[kk * 65 + nn4] = v[0]; tile[kk * 65 + nn4 + 1] = v[1]; tile[kk * 65 + nn4 + 2] = v[2]; tile[kk * 65 + nn4 + 3] = v[3]; }
;     }
;     __syncthreads();
;     {   const int nn = tid >> 3, ks = (tid & 7) * 8;
;         float v[8];
; #pragma unroll
;         for (int j = 0; j < 8; ++j) v[j] = tile[(ks + j) * 65 + nn];
;         u32x4 o; o[0] = pk_bf16(v[0], v[1]); o[1] = pk_bf16(v[2], v[3]); o[2] = pk_bf16(v[4], v[5]); o[3] = pk_bf16(v[6], v[7]);
;         *(u32x4*)(dst + (size_t)(n0 + nn) * dst_ld + dst_koff + k0 + ks) = o;
;     }
;     __syncthreads();
.LBB0_386:
	s_or_b64 exec, exec, s[20:21]
	v_add_u32_e32 v6, 0x2080, v11
	v_ashrrev_i32_e32 v8, 3, v0
	v_lshlrev_b32_e32 v0, 3, v0
	s_waitcnt vmcnt(0)
	ds_write2_b32 v6, v2, v3 offset1:1
	v_add_u32_e32 v2, 0x2088, v11
	v_and_b32_e32 v0, 56, v0
	ds_write2_b32 v2, v4, v5 offset1:1
	v_lshlrev_b32_e32 v2, 2, v8
	v_mul_u32_u24_e32 v3, 0x104, v0
	v_add3_u32 v6, 0, v2, v3
	s_waitcnt lgkmcnt(0)
	s_barrier
	ds_read2_b32 v[2:3], v6 offset1:65
	ds_read2_b32 v[4:5], v6 offset0:130 offset1:195
	v_add_u32_e32 v6, 0x400, v6
	s_waitcnt lgkmcnt(1)
	v_cvt_pk_bf16_f32 v2, v2, v3
	s_waitcnt lgkmcnt(0)
	v_cvt_pk_bf16_f32 v3, v4, v5
	ds_read2_b32 v[4:5], v6 offset0:4 offset1:69
	ds_read2_b32 v[6:7], v6 offset0:134 offset1:199
	s_waitcnt lgkmcnt(1)
	v_cvt_pk_bf16_f32 v4, v4, v5
	s_waitcnt lgkmcnt(0)
	v_cvt_pk_bf16_f32 v5, v6, v7
	v_add_u32_e32 v6, s31, v8
	v_ashrrev_i32_e32 v7, 31, v6
	v_lshlrev_b64 v[6:7], 11, v[6:7]
	v_lshl_add_u64 v[6:7], s[40:41], 0, v[6:7]
	s_ashr_i32 s43, s42, 31
	v_lshl_add_u64 v[6:7], s[42:43], 1, v[6:7]
	v_lshlrev_b32_e32 v0, 1, v0
	v_lshl_add_u64 v[6:7], v[6:7], 0, v[0:1]
	global_store_dwordx4 v[6:7], v[2:5], off
	s_waitcnt lgkmcnt(0)
	s_barrier

; DI void tr_tile(const float* src, int src_ld, int k0, int n0, int mode, bf16_t* dst, int dst_ld, int dst_koff, float* tile) {
;     const int tid = otid();
;     {   const int nn4 = (tid & 15) * 4; const int np = n0 + nn4;
;         int col = np; bool valid = true;
;         if (mode == 1) valid = np < IN_DIM;
;         if (mode == 3) valid = false;
;         if (mode == 2) { const int pn = np >> 8, bj = (np >> 7) & 1, jj = np & 127; col = bj * DFF + pn * 128 + jj; }
; #pragma unroll
;         for (int i = 0; i < 2; ++i) { const int kk = (tid >> 4) + 32 * i;
;             f32x4 v = (f32x4){0.f, 0.f, 0.f, 0.f};
;             if (valid) v = __builtin_nontemporal_load((const f32x4*)(src + (size_t)(k0 + kk) * src_ld + col));
;             tile[kk * 65 + nn4] = v[0]; tile[kk * 65 + nn4 + 1] = v[1]; tile[kk * 65 + nn4 + 2] = v[2]; tile[kk * 65 + nn4 + 3] = v[3]; }
;     }
;     __syncthreads();
;     {   const int nn = tid >> 3, ks = (tid & 7) * 8;
;         float v[8];
; #pragma unroll
;         for (int j = 0; j < 8; ++j) v[j] = tile[(ks + j) * 65 + nn];
;         u32x4 o; o[0] = pk_bf16(v[0], v[1]); o[1] = pk_bf16(v[2], v[3]); o[2] = pk_bf16(v[4], v[5]); o[3] = pk_bf16(v[6], v[7]);
;         *(u32x4*)(dst + (size_t)(n0 + nn) * dst_ld + dst_koff + k0 + ks) = o;
;     }
;     __syncthreads();
; DI void phase_convert_weights(unsigned char* ws, int l, unsigned char* lds, int t_lo, int t_hi, int bid_off) {
;     ...
;     for (int it = t_lo + (obid() - bid_off); it < t_hi; it += ogrid() - bid_off) {
;         if (it < T0) { const int nt = it / 16, kt = it % 16;
;             tr_tile(PIN(10) + (size_t)l * 1024 * IN_DIM, IN_DIM, kt * 64, nt * 64, 1, (bf16_t*)(ws + WS_WIN), 1024, 0, tile);
;         } else if (it < T1) { const int j = it - T0, nt = j / 8, kt = j % 8;
;             tr_tile(PIN(17) + (size_t)l * 512 * 1024, 1024, kt * 64, nt * 64, 0, (bf16_t*)(ws + WS_WBR), 512, 0, tile);
;         } else if (it < T2) { const int j = it - T1, nt = j / 4, kt = j % 4;
;             tr_tile(PIN(18) + (size_t)l * 256 * 1024, 1024, kt * 64, nt * 64, 0, (bf16_t*)(ws + WS_WBR) + 1024 * 512, 512, 0, tile);
;         } else if (it < T2b) { const int j = it - T2, nt = j / 4, kt = j % 4;
;             tr_tile(PIN(18), 1024, kt * 64, nt * 64, 3, (bf16_t*)(ws + WS_WBR) + 1024 * 512, 512, 256, tile);
;         } else if (it < T2c) { const int j = it - T2b, nt = j / 4, kt = j % 4;
.LBB0_388:
	s_cmpk_gt_i32 s3, 0x4ff
	s_mov_b64 s[20:21], -1
	s_cbranch_scc0 .LBB0_414
	s_cmpk_gt_u32 s3, 0x57f
	s_cbranch_scc0 .LBB0_411
	s_cmpk_gt_u32 s3, 0x5bf
	s_cbranch_scc0 .LBB0_408
	s_cmpk_gt_u32 s3, 0x5ff
	s_cbranch_scc0 .LBB0_405
	s_cmpk_gt_u32 s3, 0x63f
	s_cbranch_scc0 .LBB0_402
	s_cmpk_gt_u32 s3, 0x67f
	s_cbranch_scc0 .LBB0_399
	s_lshl_b32 s20, s3, 6
	s_and_b32 s31, s20, 0x3c0
	s_lshl_b32 s34, s3, 2
	s_cmpk_gt_u32 s3, 0x77f
	s_mov_b64 s[20:21], -1
	s_cbranch_scc0 .LBB0_396
	s_load_dwordx2 s[20:21], s[0:1], 0xa8
	v_mov_b32_e32 v8, v176
	s_waitcnt lgkmcnt(0)
	s_add_u32 s20, s20, s23
	s_addc_u32 s21, s21, s22
	s_and_b32 s35, s34, 0x3fc0
	s_addk_i32 s35, 0xe200
	s_bfe_i32 s42, s3, 0x10005
	s_lshr_b32 s43, s35, 1
	s_and_b32 s42, s42, 0xb00
	s_and_b32 s43, s43, 0x7fffff80
	v_lshlrev_b32_e32 v0, 2, v8
	s_and_b32 s37, s34, 64
	s_add_i32 s43, s43, s42
	v_and_b32_e32 v2, 60, v0
	s_or_b32 s37, s43, s37
	v_or_b32_e32 v0, s37, v2
	v_ashrrev_i32_e32 v9, 4, v8
	v_lshl_add_u64 v[6:7], v[0:1], 2, s[20:21]
	v_add_u32_e32 v0, s31, v9
	s_movk_i32 s37, 0x5800
	v_lshlrev_b32_e32 v10, 2, v2
	v_mad_i64_i32 v[2:3], s[20:21], v0, s37, v[6:7]
	global_load_dwordx4 v[2:5], v[2:3], off nt
	v_mul_lo_u32 v9, v9, s81
	v_add3_u32 v9, 0, v10, v9
	v_add_u32_e32 v0, 32, v0
	s_lshl_b32 s72, s31, 1
	v_mad_i64_i32 v[104:105], s[20:21], v0, s37, v[6:7]
	global_load_dwordx4 v[100:103], v[104:105], off nt
	s_waitcnt vmcnt(0)
	ds_write2_b32 v9, v2, v3 offset1:1
	ds_write2_b32 v9, v4, v5 offset0:2 offset1:3
	v_add_u32_e32 v0, 0x2080, v9
	s_mov_b64 s[20:21], 0
	ds_write2_b32 v0, v100, v101 offset1:1
	v_add_u32_e32 v0, 0x2088, v9
	v_lshlrev_b32_e32 v2, 3, v8
	ds_write2_b32 v0, v102, v103 offset1:1
	v_ashrrev_i32_e32 v0, 3, v8
	v_and_b32_e32 v8, 56, v2
	v_lshlrev_b32_e32 v2, 2, v0
	v_mul_u32_u24_e32 v3, 0x104, v8
	v_add3_u32 v6, 0, v2, v3
	s_waitcnt lgkmcnt(0)
	s_barrier
	ds_read2_b32 v[2:3], v6 offset1:65
	ds_read2_b32 v[4:5], v6 offset0:130 offset1:195
	v_add_u32_e32 v6, 0x400, v6
	s_waitcnt lgkmcnt(1)
	v_cvt_pk_bf16_f32 v2, v2, v3
	s_waitcnt lgkmcnt(0)
	v_cvt_pk_bf16_f32 v3, v4, v5
	ds_read2_b32 v[4:5], v6 offset0:4 offset1:69
	ds_read2_b32 v[6:7], v6 offset0:134 offset1:199
	s_waitcnt lgkmcnt(1)
	v_cvt_pk_bf16_f32 v4, v4, v5
	s_waitcnt lgkmcnt(0)
	v_cvt_pk_bf16_f32 v5, v6, v7
	v_add_u32_e32 v6, s35, v0
	v_ashrrev_i32_e32 v7, 31, v6
	v_lshlrev_b64 v[6:7], 11, v[6:7]
	v_lshl_add_u64 v[6:7], s[4:5], 0, v[6:7]
	v_lshl_add_u64 v[6:7], v[6:7], 0, s[72:73]
	v_lshlrev_b32_e32 v0, 1, v8
	v_lshl_add_u64 v[6:7], v[6:7], 0, v[0:1]
	global_store_dwordx4 v[6:7], v[2:5], off
	s_waitcnt lgkmcnt(0)
	s_barrier
.LBB0_396:
	s_andn2_b64 vcc, exec, s[20:21]
	s_cbranch_vccnz .LBB0_398
	s_load_dwordx2 s[20:21], s[0:1], 0xa0
	v_mov_b32_e32 v10, v176
	s_waitcnt lgkmcnt(0)
	s_add_u32 s20, s20, s6
	s_addc_u32 s21, s21, s7
	s_and_b32 s34, s34, 0x1fc0
	v_lshlrev_b32_e32 v0, 2, v10
	v_ashrrev_i32_e32 v11, 4, v10
	s_addk_i32 s34, 0xe600
	v_and_b32_e32 v2, 60, v0
	v_add_u32_e32 v8, s31, v11
	v_or_b32_e32 v0, s34, v2
	v_ashrrev_i32_e32 v9, 31, v8
	v_lshlrev_b32_e32 v12, 2, v2
	v_lshl_add_u64 v[6:7], v[0:1], 2, s[20:21]
	v_lshlrev_b64 v[2:3], 12, v[8:9]
	v_lshl_add_u64 v[2:3], v[6:7], 0, v[2:3]
	global_load_dwordx4 v[2:5], v[2:3], off nt
	v_mul_lo_u32 v0, v11, s81
	v_add3_u32 v0, 0, v12, v0
	s_lshl_b32 s72, s31, 1
	v_add_u32_e32 v104, 32, v8
	v_ashrrev_i32_e32 v105, 31, v104
	v_lshlrev_b64 v[104:105], 12, v[104:105]
	v_lshl_add_u64 v[104:105], v[6:7], 0, v[104:105]
	global_load_dwordx4 v[100:103], v[104:105], off nt
	s_waitcnt vmcnt(0)
	ds_write2_b32 v0, v2, v3 offset1:1
	ds_write2_b32 v0, v4, v5 offset0:2 offset1:3
	v_add_u32_e32 v6, 0x2080, v0
	v_add_u32_e32 v0, 0x2088, v0
	ds_write2_b32 v6, v100, v101 offset1:1
	v_lshlrev_b32_e32 v2, 3, v10
	ds_write2_b32 v0, v102, v103 offset1:1
	v_ashrrev_i32_e32 v0, 3, v10
	v_and_b32_e32 v8, 56, v2
	v_lshlrev_b32_e32 v2, 2, v0
	v_mul_u32_u24_e32 v3, 0x104, v8
	v_add3_u32 v6, 0, v2, v3
	s_waitcnt lgkmcnt(0)
	s_barrier
	ds_read2_b32 v[2:3], v6 offset1:65
	ds_read2_b32 v[4:5], v6 offset0:130 offset1:195
	v_add_u32_e32 v6, 0x400, v6
	s_waitcnt lgkmcnt(1)
	v_cvt_pk_bf16_f32 v2, v2, v3
	s_waitcnt lgkmcnt(0)
	v_cvt_pk_bf16_f32 v3, v4, v5
	ds_read2_b32 v[4:5], v6 offset0:4 offset1:69
	ds_read2_b32 v[6:7], v6 offset0:134 offset1:199
	s_waitcnt lgkmcnt(1)
	v_cvt_pk_bf16_f32 v4, v4, v5
	s_waitcnt lgkmcnt(0)
	v_cvt_pk_bf16_f32 v5, v6, v7
	v_add_u32_e32 v6, s34, v0
	v_ashrrev_i32_e32 v7, 31, v6
	v_lshlrev_b64 v[6:7], 11, v[6:7]
	v_lshl_add_u64 v[6:7], s[8:9], 0, v[6:7]
	v_lshl_add_u64 v[6:7], v[6:7], 0, s[72:73]
	v_lshlrev_b32_e32 v0, 1, v8
	v_lshl_add_u64 v[6:7], v[6:7], 0, v[0:1]
	global_store_dwordx4 v[6:7], v[2:5], off
	s_waitcnt lgkmcnt(0)
	s_barrier

; #define PIN(i) (((KargTbl)__builtin_amdgcn_kernarg_segment_ptr())[i])
; DI unsigned pk_bf16(float lo, float hi) { unsigned r; asm("v_cvt_pk_bf16_f32 %0, %1, %2" : "=v"(r) : "v"(lo), "v"(hi)); return r; }
; DI int otid() { int t = threadIdx.x; asm volatile("" : "+v"(t)); return t; }
; DI void tr_tile(const float* src, int src_ld, int k0, int n0, int mode, bf16_t* dst, int dst_ld, int dst_koff, float* tile) {
;     const int tid = otid();
;     {   const int nn4 = (tid & 15) * 4; const int np = n0 + nn4;
;         int col = np; bool valid = true;
;         if (mode == 1) valid = np < IN_DIM;
;         if (mode == 3) valid = false;
;         if (mode == 2) { const int pn = np >> 8, bj = (np >> 7) & 1, jj = np & 127; col = bj * DFF + pn * 128 + jj; }
; #pragma unroll
;         for (int i = 0; i < 2; ++i) { const int kk = (tid >> 4) + 32 * i;
;             f32x4 v = (f32x4){0.f, 0.f, 0.f, 0.f};
;             if (valid) v = __builtin_nontemporal_load((const f32x4*)(src + (size_t)(k0 + kk) * src_ld + col));
;             tile[kk * 65 + nn4] = v[0]; tile[kk * 65 + nn4 + 1] = v[1]; tile[kk * 65 + nn4 + 2] = v[2]; tile[kk * 65 + nn4 + 3] = v[3]; }
;     }
;     __syncthreads();
;     {   const int nn = tid >> 3, ks = (tid & 7) * 8;
;         float v[8];
; #pragma unroll
;         for (int j = 0; j < 8; ++j) v[j] = tile[(ks + j) * 65 + nn];
;         u32x4 o; o[0] = pk_bf16(v[0], v[1]); o[1] = pk_bf16(v[2], v[3]); o[2] = pk_bf16(v[4], v[5]); o[3] = pk_bf16(v[6], v[7]);
;         *(u32x4*)(dst + (size_t)(n0 + nn) * dst_ld + dst_koff + k0 + ks) = o;
;     }
;     __syncthreads();
; DI void phase_convert_weights(unsigned char* ws, int l, unsigned char* lds, int t_lo, int t_hi, int bid_off) {
;     ...
;         } else if (it < T3) { const int j = it - T2c, nt = j / 4, kt = j % 4;
;             tr_tile(PIN(19) + (size_t)l * 256 * 1024, 1024, kt * 64, nt * 64, 0, (bf16_t*)(ws + WS_WBR) + 2048 * 512, 512, 256, tile);
.LBB0_399:
	s_andn2_b64 vcc, exec, s[20:21]
	s_cbranch_vccnz .LBB0_401
	s_load_dwordx2 s[20:21], s[0:1], 0x98
	v_mov_b32_e32 v10, v176
	s_waitcnt lgkmcnt(0)
	s_add_u32 s34, s20, s10
	s_addc_u32 s35, s21, s11
	s_lshl_b32 s20, s3, 6
	s_lshl_b32 s21, s3, 4
	s_and_b32 s20, s20, 0xc0
	s_and_b32 s21, s21, 0x7fc0
	v_lshlrev_b32_e32 v0, 2, v10
	v_ashrrev_i32_e32 v11, 4, v10
	s_addk_i32 s21, 0x9c00
	v_and_b32_e32 v2, 60, v0
	v_add_u32_e32 v8, s20, v11
	v_or_b32_e32 v0, s21, v2
	v_ashrrev_i32_e32 v9, 31, v8
	v_lshlrev_b32_e32 v12, 2, v2
	v_lshl_add_u64 v[6:7], v[0:1], 2, s[34:35]
	v_lshlrev_b64 v[2:3], 12, v[8:9]
	v_lshl_add_u64 v[2:3], v[6:7], 0, v[2:3]
	global_load_dwordx4 v[2:5], v[2:3], off nt
	v_mul_lo_u32 v0, v11, s81
	v_add3_u32 v0, 0, v12, v0
	s_lshl_b32 s72, s20, 1
	v_add_u32_e32 v104, 32, v8
	v_ashrrev_i32_e32 v105, 31, v104
	v_lshlrev_b64 v[104:105], 12, v[104:105]
	v_lshl_add_u64 v[104:105], v[6:7], 0, v[104:105]
	global_load_dwordx4 v[100:103], v[104:105], off nt
	s_waitcnt vmcnt(0)
	ds_write2_b32 v0, v2, v3 offset1:1
	ds_write2_b32 v0, v4, v5 offset0:2 offset1:3
	v_add_u32_e32 v6, 0x2080, v0
	v_add_u32_e32 v0, 0x2088, v0
	ds_write2_b32 v6, v100, v101 offset1:1
	v_lshlrev_b32_e32 v2, 3, v10
	ds_write2_b32 v0, v102, v103 offset1:1
	v_ashrrev_i32_e32 v0, 3, v10
	v_and_b32_e32 v8, 56, v2
	v_lshlrev_b32_e32 v2, 2, v0
	v_mul_u32_u24_e32 v3, 0x104, v8
	v_add3_u32 v6, 0, v2, v3
	s_waitcnt lgkmcnt(0)
	s_barrier
	ds_read2_b32 v[2:3], v6 offset1:65
	ds_read2_b32 v[4:5], v6 offset0:130 offset1:195
	v_add_u32_e32 v6, 0x400, v6
	s_waitcnt lgkmcnt(1)
	v_cvt_pk_bf16_f32 v2, v2, v3
	s_waitcnt lgkmcnt(0)
	v_cvt_pk_bf16_f32 v3, v4, v5
	ds_read2_b32 v[4:5], v6 offset0:4 offset1:69
	ds_read2_b32 v[6:7], v6 offset0:134 offset1:199
	s_waitcnt lgkmcnt(1)
	v_cvt_pk_bf16_f32 v4, v4, v5
	s_waitcnt lgkmcnt(0)
	v_cvt_pk_bf16_f32 v5, v6, v7
	v_add_u32_e32 v6, s21, v0
	v_ashrrev_i32_e32 v7, 31, v6
	v_lshlrev_b64 v[6:7], 10, v[6:7]
	v_lshl_add_u64 v[6:7], s[84:85], 0, v[6:7]
	v_lshl_add_u64 v[6:7], v[6:7], 0, s[72:73]
	v_lshlrev_b32_e32 v0, 1, v8
	v_lshl_add_u64 v[6:7], v[6:7], 0, v[0:1]
	v_add_co_u32_e32 v6, vcc, 0x1562000, v6
	s_nop 1
	v_addc_co_u32_e32 v7, vcc, 0, v7, vcc
	flat_store_dwordx4 v[6:7], v[2:5] offset:512
	s_waitcnt lgkmcnt(0)
	s_barrier

; #define PIN(i) (((KargTbl)__builtin_amdgcn_kernarg_segment_ptr())[i])
; DI unsigned pk_bf16(float lo, float hi) { unsigned r; asm("v_cvt_pk_bf16_f32 %0, %1, %2" : "=v"(r) : "v"(lo), "v"(hi)); return r; }
; DI int otid() { int t = threadIdx.x; asm volatile("" : "+v"(t)); return t; }
; DI void tr_tile(const float* src, int src_ld, int k0, int n0, int mode, bf16_t* dst, int dst_ld, int dst_koff, float* tile) {
;     const int tid = otid();
;     {   const int nn4 = (tid & 15) * 4; const int np = n0 + nn4;
;         int col = np; bool valid = true;
;         if (mode == 1) valid = np < IN_DIM;
;         if (mode == 3) valid = false;
;         if (mode == 2) { const int pn = np >> 8, bj = (np >> 7) & 1, jj = np & 127; col = bj * DFF + pn * 128 + jj; }
; #pragma unroll
;         for (int i = 0; i < 2; ++i) { const int kk = (tid >> 4) + 32 * i;
;             f32x4 v = (f32x4){0.f, 0.f, 0.f, 0.f};
;             if (valid) v = __builtin_nontemporal_load((const f32x4*)(src + (size_t)(k0 + kk) * src_ld + col));
;             tile[kk * 65 + nn4] = v[0]; tile[kk * 65 + nn4 + 1] = v[1]; tile[kk * 65 + nn4 + 2] = v[2]; tile[kk * 65 + nn4 + 3] = v[3]; }
;     }
;     __syncthreads();
;     {   const int nn = tid >> 3, ks = (tid & 7) * 8;
;         float v[8];
; #pragma unroll
;         for (int j = 0; j < 8; ++j) v[j] = tile[(ks + j) * 65 + nn];
;         u32x4 o; o[0] = pk_bf16(v[0], v[1]); o[1] = pk_bf16(v[2], v[3]); o[2] = pk_bf16(v[4], v[5]); o[3] = pk_bf16(v[6], v[7]);
;         *(u32x4*)(dst + (size_t)(n0 + nn) * dst_ld + dst_koff + k0 + ks) = o;
;     }
;     __syncthreads();
; DI void phase_convert_weights(unsigned char* ws, int l, unsigned char* lds, int t_lo, int t_hi, int bid_off) {
;     ...
;         } else if (it < T2c) { const int j = it - T2b, nt = j / 4, kt = j % 4;
;             tr_tile(PIN(19), 1024, kt * 64, nt * 64, 3, (bf16_t*)(ws + WS_WBR) + 2048 * 512, 512, 0, tile);
.LBB0_402:
	s_andn2_b64 vcc, exec, s[20:21]
	s_cbranch_vccnz .LBB0_404
	v_mov_b32_e32 v0, v176
	s_load_dwordx2 s[20:21], s[0:1], 0x98
	s_waitcnt lgkmcnt(0)
	s_lshl_b32 s20, s3, 4
	v_ashrrev_i32_e32 v2, 4, v0
	v_lshlrev_b32_e32 v3, 4, v0
	v_and_b32_e32 v3, 0xf0, v3
	v_mul_lo_u32 v2, v2, s81
	v_add3_u32 v2, 0, v3, v2
	v_ashrrev_i32_e32 v8, 3, v0
	v_lshlrev_b32_e32 v0, 3, v0
	ds_write2_b32 v2, v1, v1 offset1:1
	ds_write2_b32 v2, v1, v1 offset0:2 offset1:3
	v_add_u32_e32 v3, 0x2080, v2
	v_add_u32_e32 v2, 0x2088, v2
	v_and_b32_e32 v0, 56, v0
	ds_write2_b32 v3, v1, v1 offset1:1
	ds_write2_b32 v2, v1, v1 offset1:1
	v_lshlrev_b32_e32 v2, 2, v8
	v_mul_u32_u24_e32 v3, 0x104, v0
	v_add3_u32 v6, 0, v2, v3
	s_and_b32 s20, s20, 0x7fc0
	s_waitcnt vmcnt(0) lgkmcnt(0)
	s_barrier
	ds_read2_b32 v[2:3], v6 offset1:65
	ds_read2_b32 v[4:5], v6 offset0:130 offset1:195
	v_add_u32_e32 v6, 0x400, v6
	s_addk_i32 s20, 0xa000
	s_waitcnt lgkmcnt(1)
	v_cvt_pk_bf16_f32 v2, v2, v3
	s_waitcnt lgkmcnt(0)
	v_cvt_pk_bf16_f32 v3, v4, v5
	ds_read2_b32 v[4:5], v6 offset0:4 offset1:69
	ds_read2_b32 v[6:7], v6 offset0:134 offset1:199
	s_waitcnt lgkmcnt(1)
	v_cvt_pk_bf16_f32 v4, v4, v5
	s_waitcnt lgkmcnt(0)
	v_cvt_pk_bf16_f32 v5, v6, v7
	v_add_u32_e32 v6, s20, v8
	v_ashrrev_i32_e32 v7, 31, v6
	v_lshlrev_b64 v[6:7], 10, v[6:7]
	s_lshl_b32 s20, s3, 7
	v_lshl_add_u64 v[6:7], s[12:13], 0, v[6:7]
	s_and_b32 s72, s20, 0x180
	v_lshl_add_u64 v[6:7], v[6:7], 0, s[72:73]
	v_lshlrev_b32_e32 v0, 1, v0
	v_lshl_add_u64 v[6:7], v[6:7], 0, v[0:1]
	global_store_dwordx4 v[6:7], v[2:5], off
	s_waitcnt lgkmcnt(0)
	s_barrier

; #define PIN(i) (((KargTbl)__builtin_amdgcn_kernarg_segment_ptr())[i])
; DI unsigned pk_bf16(float lo, float hi) { unsigned r; asm("v_cvt_pk_bf16_f32 %0, %1, %2" : "=v"(r) : "v"(lo), "v"(hi)); return r; }
; DI int otid() { int t = threadIdx.x; asm volatile("" : "+v"(t)); return t; }
; DI void tr_tile(const float* src, int src_ld, int k0, int n0, int mode, bf16_t* dst, int dst_ld, int dst_koff, float* tile) {
;     const int tid = otid();
;     {   const int nn4 = (tid & 15) * 4; const int np = n0 + nn4;
;         int col = np; bool valid = true;
;         if (mode == 1) valid = np < IN_DIM;
;         if (mode == 3) valid = false;
;         if (mode == 2) { const int pn = np >> 8, bj = (np >> 7) & 1, jj = np & 127; col = bj * DFF + pn * 128 + jj; }
; #pragma unroll
;         for (int i = 0; i < 2; ++i) { const int kk = (tid >> 4) + 32 * i;
;             f32x4 v = (f32x4){0.f, 0.f, 0.f, 0.f};
;             if (valid) v = __builtin_nontemporal_load((const f32x4*)(src + (size_t)(k0 + kk) * src_ld + col));
;             tile[kk * 65 + nn4] = v[0]; tile[kk * 65 + nn4 + 1] = v[1]; tile[kk * 65 + nn4 + 2] = v[2]; tile[kk * 65 + nn4 + 3] = v[3]; }
;     }
;     __syncthreads();
;     {   const int nn = tid >> 3, ks = (tid & 7) * 8;
;         float v[8];
; #pragma unroll
;         for (int j = 0; j < 8; ++j) v[j] = tile[(ks + j) * 65 + nn];
;         u32x4 o; o[0] = pk_bf16(v[0], v[1]); o[1] = pk_bf16(v[2], v[3]); o[2] = pk_bf16(v[4], v[5]); o[3] = pk_bf16(v[6], v[7]);
;         *(u32x4*)(dst + (size_t)(n0 + nn) * dst_ld + dst_koff + k0 + ks) = o;
;     }
;     __syncthreads();
; DI void phase_convert_weights(unsigned char* ws, int l, unsigned char* lds, int t_lo, int t_hi, int bid_off) {
;     ...
;         } else if (it < T2) { const int j = it - T1, nt = j / 4, kt = j % 4;
;             tr_tile(PIN(18) + (size_t)l * 256 * 1024, 1024, kt * 64, nt * 64, 0, (bf16_t*)(ws + WS_WBR) + 1024 * 512, 512, 0, tile);
.LBB0_408:
	s_andn2_b64 vcc, exec, s[20:21]
	s_cbranch_vccnz .LBB0_410
	s_load_dwordx2 s[20:21], s[0:1], 0x90
	v_mov_b32_e32 v10, v176
	s_waitcnt lgkmcnt(0)
	s_add_u32 s34, s20, s10
	s_addc_u32 s35, s21, s11
	s_lshl_b32 s20, s3, 6
	s_lshl_b32 s21, s3, 4
	s_and_b32 s20, s20, 0xc0
	s_and_b32 s21, s21, 0x7fc0
	v_lshlrev_b32_e32 v0, 2, v10
	v_ashrrev_i32_e32 v11, 4, v10
	s_addk_i32 s21, 0xa800
	v_and_b32_e32 v2, 60, v0
	v_add_u32_e32 v8, s20, v11
	v_or_b32_e32 v0, s21, v2
	v_ashrrev_i32_e32 v9, 31, v8
	v_lshlrev_b32_e32 v12, 2, v2
	v_lshl_add_u64 v[6:7], v[0:1], 2, s[34:35]
	v_lshlrev_b64 v[2:3], 12, v[8:9]
	v_lshl_add_u64 v[2:3], v[6:7], 0, v[2:3]
	global_load_dwordx4 v[2:5], v[2:3], off nt
	v_mul_lo_u32 v0, v11, s81
	v_add3_u32 v0, 0, v12, v0
	s_lshl_b32 s72, s20, 1
	v_add_u32_e32 v104, 32, v8
	v_ashrrev_i32_e32 v105, 31, v104
	v_lshlrev_b64 v[104:105], 12, v[104:105]
	v_lshl_add_u64 v[104:105], v[6:7], 0, v[104:105]
	global_load_dwordx4 v[100:103], v[104:105], off nt
	s_waitcnt vmcnt(0)
	ds_write2_b32 v0, v2, v3 offset1:1
	ds_write2_b32 v0, v4, v5 offset0:2 offset1:3
	v_add_u32_e32 v6, 0x2080, v0
	v_add_u32_e32 v0, 0x2088, v0
	ds_write2_b32 v6, v100, v101 offset1:1
	v_lshlrev_b32_e32 v2, 3, v10
	ds_write2_b32 v0, v102, v103 offset1:1
	v_ashrrev_i32_e32 v0, 3, v10
	v_and_b32_e32 v8, 56, v2
	v_lshlrev_b32_e32 v2, 2, v0
	v_mul_u32_u24_e32 v3, 0x104, v8
	v_add3_u32 v6, 0, v2, v3
	s_waitcnt lgkmcnt(0)
	s_barrier
	ds_read2_b32 v[2:3], v6 offset1:65
	ds_read2_b32 v[4:5], v6 offset0:130 offset1:195
	v_add_u32_e32 v6, 0x400, v6
	s_waitcnt lgkmcnt(1)
	v_cvt_pk_bf16_f32 v2, v2, v3
	s_waitcnt lgkmcnt(0)
	v_cvt_pk_bf16_f32 v3, v4, v5
	ds_read2_b32 v[4:5], v6 offset0:4 offset1:69
	ds_read2_b32 v[6:7], v6 offset0:134 offset1:199
	s_waitcnt lgkmcnt(1)
	v_cvt_pk_bf16_f32 v4, v4, v5
	s_waitcnt lgkmcnt(0)
	v_cvt_pk_bf16_f32 v5, v6, v7
	v_add_u32_e32 v6, s21, v0
	v_ashrrev_i32_e32 v7, 31, v6
	v_lshlrev_b64 v[6:7], 10, v[6:7]
	v_lshl_add_u64 v[6:7], s[14:15], 0, v[6:7]
	v_lshl_add_u64 v[6:7], v[6:7], 0, s[72:73]
	v_lshlrev_b32_e32 v0, 1, v8
	v_lshl_add_u64 v[6:7], v[6:7], 0, v[0:1]
	global_store_dwordx4 v[6:7], v[2:5], off
	s_waitcnt lgkmcnt(0)
	s_barrier

; #define PIN(i) (((KargTbl)__builtin_amdgcn_kernarg_segment_ptr())[i])
; DI unsigned pk_bf16(float lo, float hi) { unsigned r; asm("v_cvt_pk_bf16_f32 %0, %1, %2" : "=v"(r) : "v"(lo), "v"(hi)); return r; }
; DI int otid() { int t = threadIdx.x; asm volatile("" : "+v"(t)); return t; }
; DI void tr_tile(const float* src, int src_ld, int k0, int n0, int mode, bf16_t* dst, int dst_ld, int dst_koff, float* tile) {
;     const int tid = otid();
;     {   const int nn4 = (tid & 15) * 4; const int np = n0 + nn4;
;         int col = np; bool valid = true;
;         if (mode == 1) valid = np < IN_DIM;
;         if (mode == 3) valid = false;
;         if (mode == 2) { const int pn = np >> 8, bj = (np >> 7) & 1, jj = np & 127; col = bj * DFF + pn * 128 + jj; }
; #pragma unroll
;         for (int i = 0; i < 2; ++i) { const int kk = (tid >> 4) + 32 * i;
;             f32x4 v = (f32x4){0.f, 0.f, 0.f, 0.f};
;             if (valid) v = __builtin_nontemporal_load((const f32x4*)(src + (size_t)(k0 + kk) * src_ld + col));
;             tile[kk * 65 + nn4] = v[0]; tile[kk * 65 + nn4 + 1] = v[1]; tile[kk * 65 + nn4 + 2] = v[2]; tile[kk * 65 + nn4 + 3] = v[3]; }
;     }
;     __syncthreads();
;     {   const int nn = tid >> 3, ks = (tid & 7) * 8;
;         float v[8];
; #pragma unroll
;         for (int j = 0; j < 8; ++j) v[j] = tile[(ks + j) * 65 + nn];
;         u32x4 o; o[0] = pk_bf16(v[0], v[1]); o[1] = pk_bf16(v[2], v[3]); o[2] = pk_bf16(v[4], v[5]); o[3] = pk_bf16(v[6], v[7]);
;         *(u32x4*)(dst + (size_t)(n0 + nn) * dst_ld + dst_koff + k0 + ks) = o;
;     }
;     __syncthreads();
; DI void phase_convert_weights(unsigned char* ws, int l, unsigned char* lds, int t_lo, int t_hi, int bid_off) {
;     ...
;         } else if (it < T1) { const int j = it - T0, nt = j / 8, kt = j % 8;
;             tr_tile(PIN(17) + (size_t)l * 512 * 1024, 1024, kt * 64, nt * 64, 0, (bf16_t*)(ws + WS_WBR), 512, 0, tile);
.LBB0_411:
	s_andn2_b64 vcc, exec, s[20:21]
	s_cbranch_vccnz .LBB0_413
	s_load_dwordx2 s[20:21], s[0:1], 0x88
	v_mov_b32_e32 v10, v176
	s_waitcnt lgkmcnt(0)
	s_add_u32 s34, s20, s16
	s_addc_u32 s35, s21, s17
	s_lshl_b32 s20, s3, 6
	s_lshl_b32 s21, s3, 3
	s_and_b32 s20, s20, 0x1c0
	s_and_b32 s21, s21, 0x3fc0
	v_lshlrev_b32_e32 v0, 2, v10
	v_ashrrev_i32_e32 v11, 4, v10
	s_addk_i32 s21, 0xd800
	v_and_b32_e32 v2, 60, v0
	v_add_u32_e32 v8, s20, v11
	v_or_b32_e32 v0, s21, v2
	v_ashrrev_i32_e32 v9, 31, v8
	v_lshlrev_b32_e32 v12, 2, v2
	v_lshl_add_u64 v[6:7], v[0:1], 2, s[34:35]
	v_lshlrev_b64 v[2:3], 12, v[8:9]
	v_lshl_add_u64 v[2:3], v[6:7], 0, v[2:3]
	global_load_dwordx4 v[2:5], v[2:3], off nt
	v_mul_lo_u32 v0, v11, s81
	v_add3_u32 v0, 0, v12, v0
	s_lshl_b32 s72, s20, 1
	v_add_u32_e32 v104, 32, v8
	v_ashrrev_i32_e32 v105, 31, v104
	v_lshlrev_b64 v[104:105], 12, v[104:105]
	v_lshl_add_u64 v[104:105], v[6:7], 0, v[104:105]
	global_load_dwordx4 v[100:103], v[104:105], off nt
	s_waitcnt vmcnt(0)
	ds_write2_b32 v0, v2, v3 offset1:1
	ds_write2_b32 v0, v4, v5 offset0:2 offset1:3
	v_add_u32_e32 v6, 0x2080, v0
	v_add_u32_e32 v0, 0x2088, v0
	ds_write2_b32 v6, v100, v101 offset1:1
	v_lshlrev_b32_e32 v2, 3, v10
	ds_write2_b32 v0, v102, v103 offset1:1
	v_ashrrev_i32_e32 v0, 3, v10
	v_and_b32_e32 v8, 56, v2
	v_lshlrev_b32_e32 v2, 2, v0
	v_mul_u32_u24_e32 v3, 0x104, v8
	v_add3_u32 v6, 0, v2, v3
	s_waitcnt lgkmcnt(0)
	s_barrier
	ds_read2_b32 v[2:3], v6 offset1:65
	ds_read2_b32 v[4:5], v6 offset0:130 offset1:195
	v_add_u32_e32 v6, 0x400, v6
	s_waitcnt lgkmcnt(1)
	v_cvt_pk_bf16_f32 v2, v2, v3
	s_waitcnt lgkmcnt(0)
	v_cvt_pk_bf16_f32 v3, v4, v5
	ds_read2_b32 v[4:5], v6 offset0:4 offset1:69
	ds_read2_b32 v[6:7], v6 offset0:134 offset1:199
	s_waitcnt lgkmcnt(1)
	v_cvt_pk_bf16_f32 v4, v4, v5
	s_waitcnt lgkmcnt(0)
	v_cvt_pk_bf16_f32 v5, v6, v7
	v_add_u32_e32 v6, s21, v0
	v_ashrrev_i32_e32 v7, 31, v6
	v_lshlrev_b64 v[6:7], 10, v[6:7]
	v_lshl_add_u64 v[6:7], s[18:19], 0, v[6:7]
	v_lshl_add_u64 v[6:7], v[6:7], 0, s[72:73]
	v_lshlrev_b32_e32 v0, 1, v8
	v_lshl_add_u64 v[6:7], v[6:7], 0, v[0:1]
	global_store_dwordx4 v[6:7], v[2:5], off
	s_waitcnt lgkmcnt(0)
	s_barrier

; DI unsigned pk_bf16(float lo, float hi) { unsigned r; asm("v_cvt_pk_bf16_f32 %0, %1, %2" : "=v"(r) : "v"(lo), "v"(hi)); return r; }
; DI void tr_tile(const float* src, int src_ld, int k0, int n0, int mode, bf16_t* dst, int dst_ld, int dst_koff, float* tile) {
;     ...
;             tile[kk * 65 + nn4] = v[0]; tile[kk * 65 + nn4 + 1] = v[1]; tile[kk * 65 + nn4 + 2] = v[2]; tile[kk * 65 + nn4 + 3] = v[3]; }
;     }
;     __syncthreads();
;     {   const int nn = tid >> 3, ks = (tid & 7) * 8;
;         float v[8];
; #pragma unroll
;         for (int j = 0; j < 8; ++j) v[j] = tile[(ks + j) * 65 + nn];
;         u32x4 o; o[0] = pk_bf16(v[0], v[1]); o[1] = pk_bf16(v[2], v[3]); o[2] = pk_bf16(v[4], v[5]); o[3] = pk_bf16(v[6], v[7]);
;         *(u32x4*)(dst + (size_t)(n0 + nn) * dst_ld + dst_koff + k0 + ks) = o;
;     }
;     __syncthreads();
.LBB0_509:
	s_or_b64 exec, exec, s[20:21]
	v_add_u32_e32 v6, 0x2080, v11
	v_ashrrev_i32_e32 v8, 3, v0
	v_lshlrev_b32_e32 v0, 3, v0
	s_waitcnt vmcnt(0)
	ds_write2_b32 v6, v2, v3 offset1:1
	v_add_u32_e32 v2, 0x2088, v11
	v_and_b32_e32 v0, 56, v0
	ds_write2_b32 v2, v4, v5 offset1:1
	v_lshlrev_b32_e32 v2, 2, v8
	v_mul_u32_u24_e32 v3, 0x104, v0
	v_add3_u32 v6, 0, v2, v3
	s_waitcnt lgkmcnt(0)
	s_barrier
	ds_read2_b32 v[2:3], v6 offset1:65
	ds_read2_b32 v[4:5], v6 offset0:130 offset1:195
	v_add_u32_e32 v6, 0x400, v6
	s_waitcnt lgkmcnt(1)
	v_cvt_pk_bf16_f32 v2, v2, v3
	s_waitcnt lgkmcnt(0)
	v_cvt_pk_bf16_f32 v3, v4, v5
	ds_read2_b32 v[4:5], v6 offset0:4 offset1:69
	ds_read2_b32 v[6:7], v6 offset0:134 offset1:199
	s_waitcnt lgkmcnt(1)
	v_cvt_pk_bf16_f32 v4, v4, v5
	s_waitcnt lgkmcnt(0)
	v_cvt_pk_bf16_f32 v5, v6, v7
	v_add_u32_e32 v6, s31, v8
	v_ashrrev_i32_e32 v7, 31, v6
	v_lshlrev_b64 v[6:7], 11, v[6:7]
	v_lshl_add_u64 v[6:7], s[42:43], 0, v[6:7]
	s_ashr_i32 s45, s44, 31
	v_lshl_add_u64 v[6:7], s[44:45], 1, v[6:7]
	v_lshlrev_b32_e32 v0, 1, v0
	v_lshl_add_u64 v[6:7], v[6:7], 0, v[0:1]
	global_store_dwordx4 v[6:7], v[2:5], off
	s_waitcnt lgkmcnt(0)
	s_barrier

; #define PIN(i) (((KargTbl)__builtin_amdgcn_kernarg_segment_ptr())[i])
; DI unsigned pk_bf16(float lo, float hi) { unsigned r; asm("v_cvt_pk_bf16_f32 %0, %1, %2" : "=v"(r) : "v"(lo), "v"(hi)); return r; }
; DI int otid() { int t = threadIdx.x; asm volatile("" : "+v"(t)); return t; }
; DI void tr_tile(const float* src, int src_ld, int k0, int n0, int mode, bf16_t* dst, int dst_ld, int dst_koff, float* tile) {
;     const int tid = otid();
;     {   const int nn4 = (tid & 15) * 4; const int np = n0 + nn4;
;         int col = np; bool valid = true;
;         if (mode == 1) valid = np < IN_DIM;
;         if (mode == 3) valid = false;
;         if (mode == 2) { const int pn = np >> 8, bj = (np >> 7) & 1, jj = np & 127; col = bj * DFF + pn * 128 + jj; }
; #pragma unroll
;         for (int i = 0; i < 2; ++i) { const int kk = (tid >> 4) + 32 * i;
;             f32x4 v = (f32x4){0.f, 0.f, 0.f, 0.f};
;             if (valid) v = __builtin_nontemporal_load((const f32x4*)(src + (size_t)(k0 + kk) * src_ld + col));
;             tile[kk * 65 + nn4] = v[0]; tile[kk * 65 + nn4 + 1] = v[1]; tile[kk * 65 + nn4 + 2] = v[2]; tile[kk * 65 + nn4 + 3] = v[3]; }
;     }
;     __syncthreads();
;     {   const int nn = tid >> 3, ks = (tid & 7) * 8;
;         float v[8];
; #pragma unroll
;         for (int j = 0; j < 8; ++j) v[j] = tile[(ks + j) * 65 + nn];
;         u32x4 o; o[0] = pk_bf16(v[0], v[1]); o[1] = pk_bf16(v[2], v[3]); o[2] = pk_bf16(v[4], v[5]); o[3] = pk_bf16(v[6], v[7]);
;         *(u32x4*)(dst + (size_t)(n0 + nn) * dst_ld + dst_koff + k0 + ks) = o;
;     }
;     __syncthreads();
; DI void phase_convert_weights(unsigned char* ws, int l, unsigned char* lds, int t_lo, int t_hi, int bid_off) {
;     ...
;         } else if (it < T5) { const int j = it - T4, nt = j / 16, kt = j % 16;
;             tr_tile(PIN(21) + (size_t)l * 1024 * UPN, UPN, kt * 64, nt * 64, 2, (bf16_t*)(ws + WS_WUP), 1024, 0, tile);
;         } else { const int j = it - T5, nt = j / 44, kt = j % 44;
;             tr_tile(PIN(24) + (size_t)l * DFF * 1024, 1024, kt * 64, nt * 64, 0, (bf16_t*)(ws + WS_WDN), DFF, 0, tile);
.LBB0_511:
	s_cmpk_gt_i32 s3, 0x4ff
	s_mov_b64 s[20:21], -1
	s_cbranch_scc0 .LBB0_541
	s_cmpk_gt_u32 s3, 0x57f
	s_cbranch_scc0 .LBB0_538
	s_cmpk_gt_u32 s3, 0x5bf
	s_cbranch_scc0 .LBB0_535
	s_cmpk_gt_u32 s3, 0x5ff
	s_cbranch_scc0 .LBB0_532
	s_cmpk_gt_u32 s3, 0x63f
	s_cbranch_scc0 .LBB0_529
	s_cmpk_gt_u32 s3, 0x67f
	s_cbranch_scc0 .LBB0_526
	s_cmpk_gt_u32 s3, 0x77f
	s_cbranch_scc0 .LBB0_523
	s_cmpk_gt_u32 s3, 0xcff
	s_cbranch_scc0 .LBB0_520
	s_add_i32 s20, s3, 0xf300
	s_and_b32 s21, s20, 0xffff
	s_mul_i32 s21, s21, 0xba2f
	s_lshr_b32 s31, s21, 21
	s_mul_i32 s21, s31, 44
	s_sub_i32 s37, s20, s21
	s_load_dwordx2 s[20:21], s[0:1], 0xc0
	v_mov_b32_e32 v10, v176
	s_waitcnt lgkmcnt(0)
	s_add_u32 s44, s20, s23
	s_addc_u32 s45, s21, s22
	s_lshl_b32 s20, s37, 6
	v_lshlrev_b32_e32 v0, 2, v10
	s_and_b32 s20, s20, 0xffc0
	s_lshl_b32 s21, s31, 6
	v_and_b32_e32 v0, 60, v0
	v_ashrrev_i32_e32 v11, 4, v10
	v_or_b32_e32 v2, s21, v0
	v_add_u32_e32 v8, s20, v11
	v_lshlrev_b32_e32 v12, 2, v0
	v_lshlrev_b32_e32 v0, 2, v2
	v_ashrrev_i32_e32 v9, 31, v8
	v_lshl_add_u64 v[6:7], s[44:45], 0, v[0:1]
	v_lshlrev_b64 v[2:3], 12, v[8:9]
	v_lshl_add_u64 v[2:3], v[6:7], 0, v[2:3]
	global_load_dwordx4 v[2:5], v[2:3], off nt
	v_mul_lo_u32 v0, v11, s81
	v_add3_u32 v0, 0, v12, v0
	s_lshl_b32 s72, s20, 1
	v_add_u32_e32 v104, 32, v8
	v_ashrrev_i32_e32 v105, 31, v104
	v_lshlrev_b64 v[104:105], 12, v[104:105]
	v_lshl_add_u64 v[104:105], v[6:7], 0, v[104:105]
	global_load_dwordx4 v[100:103], v[104:105], off nt
	s_waitcnt vmcnt(0)
	ds_write2_b32 v0, v2, v3 offset1:1
	ds_write2_b32 v0, v4, v5 offset0:2 offset1:3
	v_add_u32_e32 v6, 0x2080, v0
	v_add_u32_e32 v0, 0x2088, v0
	ds_write2_b32 v6, v100, v101 offset1:1
	v_lshlrev_b32_e32 v2, 3, v10
	ds_write2_b32 v0, v102, v103 offset1:1
	v_ashrrev_i32_e32 v0, 3, v10
	v_and_b32_e32 v8, 56, v2
	v_lshlrev_b32_e32 v2, 2, v0
	v_mul_u32_u24_e32 v3, 0x104, v8
	v_add3_u32 v6, 0, v2, v3
	s_waitcnt lgkmcnt(0)
	s_barrier
	ds_read2_b32 v[2:3], v6 offset1:65
	ds_read2_b32 v[4:5], v6 offset0:130 offset1:195
	v_add_u32_e32 v6, 0x400, v6
	s_waitcnt lgkmcnt(1)
	v_cvt_pk_bf16_f32 v2, v2, v3
	s_waitcnt lgkmcnt(0)
	v_cvt_pk_bf16_f32 v3, v4, v5
	ds_read2_b32 v[4:5], v6 offset0:4 offset1:69
	ds_read2_b32 v[6:7], v6 offset0:134 offset1:199
	s_waitcnt lgkmcnt(1)
	v_cvt_pk_bf16_f32 v4, v4, v5
	s_waitcnt lgkmcnt(0)
	v_cvt_pk_bf16_f32 v5, v6, v7
	v_add_u32_e32 v0, s21, v0
	v_mov_b64_e32 v[6:7], s[4:5]
	s_movk_i32 s21, 0x1600
	v_mad_i64_i32 v[6:7], s[44:45], v0, s21, v[6:7]
	v_lshl_add_u64 v[6:7], v[6:7], 0, s[72:73]
	v_lshlrev_b32_e32 v0, 1, v8
	v_lshl_add_u64 v[6:7], v[6:7], 0, v[0:1]
	global_store_dwordx4 v[6:7], v[2:5], off
	s_waitcnt lgkmcnt(0)
	s_barrier
	s_mov_b64 s[20:21], 0
.LBB0_520:
	s_andn2_b64 vcc, exec, s[20:21]
	s_cbranch_vccnz .LBB0_522
	s_load_dwordx2 s[20:21], s[0:1], 0xa8
	v_mov_b32_e32 v8, v176
	s_waitcnt lgkmcnt(0)
	s_add_u32 s44, s20, s29
	s_addc_u32 s45, s21, s24
	s_lshl_b32 s21, s3, 2
	s_and_b32 s31, s21, 0x3fc0
	s_addk_i32 s31, 0xe200
	s_bfe_i32 s37, s3, 0x10005
	s_lshr_b32 s46, s31, 1
	s_and_b32 s37, s37, 0xb00
	s_and_b32 s46, s46, 0x7fffff80
	v_lshlrev_b32_e32 v0, 2, v8
	s_and_b32 s21, s21, 64
	s_add_i32 s46, s46, s37
	s_lshl_b32 s20, s3, 6
	v_and_b32_e32 v2, 60, v0
	s_or_b32 s21, s46, s21
	s_and_b32 s20, s20, 0x3c0
	v_or_b32_e32 v0, s21, v2
	v_ashrrev_i32_e32 v9, 4, v8
	v_lshl_add_u64 v[6:7], v[0:1], 2, s[44:45]
	v_add_u32_e32 v0, s20, v9
	s_movk_i32 s21, 0x5800
	v_lshlrev_b32_e32 v10, 2, v2
	v_mad_i64_i32 v[2:3], s[44:45], v0, s21, v[6:7]
	global_load_dwordx4 v[2:5], v[2:3], off nt
	v_mul_lo_u32 v9, v9, s81
	v_add3_u32 v9, 0, v10, v9
	v_add_u32_e32 v0, 32, v0
	s_lshl_b32 s72, s20, 1
	v_mad_i64_i32 v[104:105], s[44:45], v0, s21, v[6:7]
	global_load_dwordx4 v[100:103], v[104:105], off nt
	s_waitcnt vmcnt(0)
	ds_write2_b32 v9, v2, v3 offset1:1
	ds_write2_b32 v9, v4, v5 offset0:2 offset1:3
	v_add_u32_e32 v0, 0x2080, v9
	ds_write2_b32 v0, v100, v101 offset1:1
	v_add_u32_e32 v0, 0x2088, v9
	v_lshlrev_b32_e32 v2, 3, v8
	ds_write2_b32 v0, v102, v103 offset1:1
	v_ashrrev_i32_e32 v0, 3, v8
	v_and_b32_e32 v8, 56, v2
	v_lshlrev_b32_e32 v2, 2, v0
	v_mul_u32_u24_e32 v3, 0x104, v8
	v_add3_u32 v6, 0, v2, v3
	s_waitcnt lgkmcnt(0)
	s_barrier
	ds_read2_b32 v[2:3], v6 offset1:65
	ds_read2_b32 v[4:5], v6 offset0:130 offset1:195
	v_add_u32_e32 v6, 0x400, v6
	s_waitcnt lgkmcnt(1)
	v_cvt_pk_bf16_f32 v2, v2, v3
	s_waitcnt lgkmcnt(0)
	v_cvt_pk_bf16_f32 v3, v4, v5
	ds_read2_b32 v[4:5], v6 offset0:4 offset1:69
	ds_read2_b32 v[6:7], v6 offset0:134 offset1:199
	s_waitcnt lgkmcnt(1)
	v_cvt_pk_bf16_f32 v4, v4, v5
	s_waitcnt lgkmcnt(0)
	v_cvt_pk_bf16_f32 v5, v6, v7
	v_add_u32_e32 v6, s31, v0
	v_ashrrev_i32_e32 v7, 31, v6
	v_lshlrev_b64 v[6:7], 11, v[6:7]
	v_lshl_add_u64 v[6:7], s[6:7], 0, v[6:7]
	v_lshl_add_u64 v[6:7], v[6:7], 0, s[72:73]
	v_lshlrev_b32_e32 v0, 1, v8
	v_lshl_add_u64 v[6:7], v[6:7], 0, v[0:1]
	global_store_dwordx4 v[6:7], v[2:5], off
	s_waitcnt lgkmcnt(0)
	s_barrier

; #define PIN(i) (((KargTbl)__builtin_amdgcn_kernarg_segment_ptr())[i])
; DI unsigned pk_bf16(float lo, float hi) { unsigned r; asm("v_cvt_pk_bf16_f32 %0, %1, %2" : "=v"(r) : "v"(lo), "v"(hi)); return r; }
; DI int otid() { int t = threadIdx.x; asm volatile("" : "+v"(t)); return t; }
; DI void tr_tile(const float* src, int src_ld, int k0, int n0, int mode, bf16_t* dst, int dst_ld, int dst_koff, float* tile) {
;     const int tid = otid();
;     {   const int nn4 = (tid & 15) * 4; const int np = n0 + nn4;
;         int col = np; bool valid = true;
;         if (mode == 1) valid = np < IN_DIM;
;         if (mode == 3) valid = false;
;         if (mode == 2) { const int pn = np >> 8, bj = (np >> 7) & 1, jj = np & 127; col = bj * DFF + pn * 128 + jj; }
; #pragma unroll
;         for (int i = 0; i < 2; ++i) { const int kk = (tid >> 4) + 32 * i;
;             f32x4 v = (f32x4){0.f, 0.f, 0.f, 0.f};
;             if (valid) v = __builtin_nontemporal_load((const f32x4*)(src + (size_t)(k0 + kk) * src_ld + col));
;             tile[kk * 65 + nn4] = v[0]; tile[kk * 65 + nn4 + 1] = v[1]; tile[kk * 65 + nn4 + 2] = v[2]; tile[kk * 65 + nn4 + 3] = v[3]; }
;     }
;     __syncthreads();
;     {   const int nn = tid >> 3, ks = (tid & 7) * 8;
;         float v[8];
; #pragma unroll
;         for (int j = 0; j < 8; ++j) v[j] = tile[(ks + j) * 65 + nn];
;         u32x4 o; o[0] = pk_bf16(v[0], v[1]); o[1] = pk_bf16(v[2], v[3]); o[2] = pk_bf16(v[4], v[5]); o[3] = pk_bf16(v[6], v[7]);
;         *(u32x4*)(dst + (size_t)(n0 + nn) * dst_ld + dst_koff + k0 + ks) = o;
;     }
;     __syncthreads();
; DI void phase_convert_weights(unsigned char* ws, int l, unsigned char* lds, int t_lo, int t_hi, int bid_off) {
;     ...
;         } else if (it < T4) { const int j = it - T3, nt = j / 16, kt = j % 16;
;             tr_tile(PIN(20) + (size_t)l * 1024 * 1024, 1024, kt * 64, nt * 64, 0, (bf16_t*)(ws + WS_WO), 1024, 0, tile);
.LBB0_523:
	s_andn2_b64 vcc, exec, s[20:21]
	s_cbranch_vccnz .LBB0_525
	s_load_dwordx2 s[20:21], s[0:1], 0xa0
	v_mov_b32_e32 v10, v176
	s_waitcnt lgkmcnt(0)
	s_add_u32 s44, s20, s8
	s_addc_u32 s45, s21, s9
	s_lshl_b32 s20, s3, 6
	s_lshl_b32 s21, s3, 2
	s_and_b32 s20, s20, 0x3c0
	s_and_b32 s21, s21, 0x1fc0
	v_lshlrev_b32_e32 v0, 2, v10
	v_ashrrev_i32_e32 v11, 4, v10
	s_addk_i32 s21, 0xe600
	v_and_b32_e32 v2, 60, v0
	v_add_u32_e32 v8, s20, v11
	v_or_b32_e32 v0, s21, v2
	v_ashrrev_i32_e32 v9, 31, v8
	v_lshlrev_b32_e32 v12, 2, v2
	v_lshl_add_u64 v[6:7], v[0:1], 2, s[44:45]
	v_lshlrev_b64 v[2:3], 12, v[8:9]
	v_lshl_add_u64 v[2:3], v[6:7], 0, v[2:3]
	global_load_dwordx4 v[2:5], v[2:3], off nt
	v_mul_lo_u32 v0, v11, s81
	v_add3_u32 v0, 0, v12, v0
	s_lshl_b32 s72, s20, 1
	v_add_u32_e32 v104, 32, v8
	v_ashrrev_i32_e32 v105, 31, v104
	v_lshlrev_b64 v[104:105], 12, v[104:105]
	v_lshl_add_u64 v[104:105], v[6:7], 0, v[104:105]
	global_load_dwordx4 v[100:103], v[104:105], off nt
	s_waitcnt vmcnt(0)
	ds_write2_b32 v0, v2, v3 offset1:1
	ds_write2_b32 v0, v4, v5 offset0:2 offset1:3
	v_add_u32_e32 v6, 0x2080, v0
	v_add_u32_e32 v0, 0x2088, v0
	ds_write2_b32 v6, v100, v101 offset1:1
	v_lshlrev_b32_e32 v2, 3, v10
	ds_write2_b32 v0, v102, v103 offset1:1
	v_ashrrev_i32_e32 v0, 3, v10
	v_and_b32_e32 v8, 56, v2
	v_lshlrev_b32_e32 v2, 2, v0
	v_mul_u32_u24_e32 v3, 0x104, v8
	v_add3_u32 v6, 0, v2, v3
	s_waitcnt lgkmcnt(0)
	s_barrier
	ds_read2_b32 v[2:3], v6 offset1:65
	ds_read2_b32 v[4:5], v6 offset0:130 offset1:195
	v_add_u32_e32 v6, 0x400, v6
	s_waitcnt lgkmcnt(1)
	v_cvt_pk_bf16_f32 v2, v2, v3
	s_waitcnt lgkmcnt(0)
	v_cvt_pk_bf16_f32 v3, v4, v5
	ds_read2_b32 v[4:5], v6 offset0:4 offset1:69
	ds_read2_b32 v[6:7], v6 offset0:134 offset1:199
	s_waitcnt lgkmcnt(1)
	v_cvt_pk_bf16_f32 v4, v4, v5
	s_waitcnt lgkmcnt(0)
	v_cvt_pk_bf16_f32 v5, v6, v7
	v_add_u32_e32 v6, s21, v0
	v_ashrrev_i32_e32 v7, 31, v6
	v_lshlrev_b64 v[6:7], 11, v[6:7]
	v_lshl_add_u64 v[6:7], s[10:11], 0, v[6:7]
	v_lshl_add_u64 v[6:7], v[6:7], 0, s[72:73]
	v_lshlrev_b32_e32 v0, 1, v8
	v_lshl_add_u64 v[6:7], v[6:7], 0, v[0:1]
	global_store_dwordx4 v[6:7], v[2:5], off
	s_waitcnt lgkmcnt(0)
	s_barrier

; #define PIN(i) (((KargTbl)__builtin_amdgcn_kernarg_segment_ptr())[i])
; DI unsigned pk_bf16(float lo, float hi) { unsigned r; asm("v_cvt_pk_bf16_f32 %0, %1, %2" : "=v"(r) : "v"(lo), "v"(hi)); return r; }
; DI int otid() { int t = threadIdx.x; asm volatile("" : "+v"(t)); return t; }
; DI void tr_tile(const float* src, int src_ld, int k0, int n0, int mode, bf16_t* dst, int dst_ld, int dst_koff, float* tile) {
;     const int tid = otid();
;     {   const int nn4 = (tid & 15) * 4; const int np = n0 + nn4;
;         int col = np; bool valid = true;
;         if (mode == 1) valid = np < IN_DIM;
;         if (mode == 3) valid = false;
;         if (mode == 2) { const int pn = np >> 8, bj = (np >> 7) & 1, jj = np & 127; col = bj * DFF + pn * 128 + jj; }
; #pragma unroll
;         for (int i = 0; i < 2; ++i) { const int kk = (tid >> 4) + 32 * i;
;             f32x4 v = (f32x4){0.f, 0.f, 0.f, 0.f};
;             if (valid) v = __builtin_nontemporal_load((const f32x4*)(src + (size_t)(k0 + kk) * src_ld + col));
;             tile[kk * 65 + nn4] = v[0]; tile[kk * 65 + nn4 + 1] = v[1]; tile[kk * 65 + nn4 + 2] = v[2]; tile[kk * 65 + nn4 + 3] = v[3]; }
;     }
;     __syncthreads();
;     {   const int nn = tid >> 3, ks = (tid & 7) * 8;
;         float v[8];
; #pragma unroll
;         for (int j = 0; j < 8; ++j) v[j] = tile[(ks + j) * 65 + nn];
;         u32x4 o; o[0] = pk_bf16(v[0], v[1]); o[1] = pk_bf16(v[2], v[3]); o[2] = pk_bf16(v[4], v[5]); o[3] = pk_bf16(v[6], v[7]);
;         *(u32x4*)(dst + (size_t)(n0 + nn) * dst_ld + dst_koff + k0 + ks) = o;
;     }
;     __syncthreads();
; DI void phase_convert_weights(unsigned char* ws, int l, unsigned char* lds, int t_lo, int t_hi, int bid_off) {
;     ...
;         } else if (it < T3) { const int j = it - T2c, nt = j / 4, kt = j % 4;
;             tr_tile(PIN(19) + (size_t)l * 256 * 1024, 1024, kt * 64, nt * 64, 0, (bf16_t*)(ws + WS_WBR) + 2048 * 512, 512, 256, tile);
.LBB0_526:
	s_andn2_b64 vcc, exec, s[20:21]
	s_cbranch_vccnz .LBB0_528
	s_load_dwordx2 s[20:21], s[0:1], 0x98
	v_mov_b32_e32 v10, v176
	s_waitcnt lgkmcnt(0)
	s_add_u32 s44, s20, s12
	s_addc_u32 s45, s21, s13
	s_lshl_b32 s20, s3, 6
	s_lshl_b32 s21, s3, 4
	s_and_b32 s20, s20, 0xc0
	s_and_b32 s21, s21, 0x7fc0
	v_lshlrev_b32_e32 v0, 2, v10
	v_ashrrev_i32_e32 v11, 4, v10
	s_addk_i32 s21, 0x9c00
	v_and_b32_e32 v2, 60, v0
	v_add_u32_e32 v8, s20, v11
	v_or_b32_e32 v0, s21, v2
	v_ashrrev_i32_e32 v9, 31, v8
	v_lshlrev_b32_e32 v12, 2, v2
	v_lshl_add_u64 v[6:7], v[0:1], 2, s[44:45]
	v_lshlrev_b64 v[2:3], 12, v[8:9]
	v_lshl_add_u64 v[2:3], v[6:7], 0, v[2:3]
	global_load_dwordx4 v[2:5], v[2:3], off nt
	v_mul_lo_u32 v0, v11, s81
	v_add3_u32 v0, 0, v12, v0
	s_lshl_b32 s72, s20, 1
	v_add_u32_e32 v104, 32, v8
	v_ashrrev_i32_e32 v105, 31, v104
	v_lshlrev_b64 v[104:105], 12, v[104:105]
	v_lshl_add_u64 v[104:105], v[6:7], 0, v[104:105]
	global_load_dwordx4 v[100:103], v[104:105], off nt
	s_waitcnt vmcnt(0)
	ds_write2_b32 v0, v2, v3 offset1:1
	ds_write2_b32 v0, v4, v5 offset0:2 offset1:3
	v_add_u32_e32 v6, 0x2080, v0
	v_add_u32_e32 v0, 0x2088, v0
	ds_write2_b32 v6, v100, v101 offset1:1
	v_lshlrev_b32_e32 v2, 3, v10
	ds_write2_b32 v0, v102, v103 offset1:1
	v_ashrrev_i32_e32 v0, 3, v10
	v_and_b32_e32 v8, 56, v2
	v_lshlrev_b32_e32 v2, 2, v0
	v_mul_u32_u24_e32 v3, 0x104, v8
	v_add3_u32 v6, 0, v2, v3
	s_waitcnt lgkmcnt(0)
	s_barrier
	ds_read2_b32 v[2:3], v6 offset1:65
	ds_read2_b32 v[4:5], v6 offset0:130 offset1:195
	v_add_u32_e32 v6, 0x400, v6
	s_waitcnt lgkmcnt(1)
	v_cvt_pk_bf16_f32 v2, v2, v3
	s_waitcnt lgkmcnt(0)
	v_cvt_pk_bf16_f32 v3, v4, v5
	ds_read2_b32 v[4:5], v6 offset0:4 offset1:69
	ds_read2_b32 v[6:7], v6 offset0:134 offset1:199
	s_waitcnt lgkmcnt(1)
	v_cvt_pk_bf16_f32 v4, v4, v5
	s_waitcnt lgkmcnt(0)
	v_cvt_pk_bf16_f32 v5, v6, v7
	v_add_u32_e32 v6, s21, v0
	v_ashrrev_i32_e32 v7, 31, v6
	v_lshlrev_b64 v[6:7], 10, v[6:7]
	v_lshl_add_u64 v[6:7], s[84:85], 0, v[6:7]
	v_lshl_add_u64 v[6:7], v[6:7], 0, s[72:73]
	v_lshlrev_b32_e32 v0, 1, v8
	v_lshl_add_u64 v[6:7], v[6:7], 0, v[0:1]
	v_add_co_u32_e32 v6, vcc, 0x1562000, v6
	s_nop 1
	v_addc_co_u32_e32 v7, vcc, 0, v7, vcc
	flat_store_dwordx4 v[6:7], v[2:5] offset:512
	s_waitcnt lgkmcnt(0)
	s_barrier

; #define PIN(i) (((KargTbl)__builtin_amdgcn_kernarg_segment_ptr())[i])
; DI unsigned pk_bf16(float lo, float hi) { unsigned r; asm("v_cvt_pk_bf16_f32 %0, %1, %2" : "=v"(r) : "v"(lo), "v"(hi)); return r; }
; DI int otid() { int t = threadIdx.x; asm volatile("" : "+v"(t)); return t; }
; DI void tr_tile(const float* src, int src_ld, int k0, int n0, int mode, bf16_t* dst, int dst_ld, int dst_koff, float* tile) {
;     const int tid = otid();
;     {   const int nn4 = (tid & 15) * 4; const int np = n0 + nn4;
;         int col = np; bool valid = true;
;         if (mode == 1) valid = np < IN_DIM;
;         if (mode == 3) valid = false;
;         if (mode == 2) { const int pn = np >> 8, bj = (np >> 7) & 1, jj = np & 127; col = bj * DFF + pn * 128 + jj; }
; #pragma unroll
;         for (int i = 0; i < 2; ++i) { const int kk = (tid >> 4) + 32 * i;
;             f32x4 v = (f32x4){0.f, 0.f, 0.f, 0.f};
;             if (valid) v = __builtin_nontemporal_load((const f32x4*)(src + (size_t)(k0 + kk) * src_ld + col));
;             tile[kk * 65 + nn4] = v[0]; tile[kk * 65 + nn4 + 1] = v[1]; tile[kk * 65 + nn4 + 2] = v[2]; tile[kk * 65 + nn4 + 3] = v[3]; }
;     }
;     __syncthreads();
;     {   const int nn = tid >> 3, ks = (tid & 7) * 8;
;         float v[8];
; #pragma unroll
;         for (int j = 0; j < 8; ++j) v[j] = tile[(ks + j) * 65 + nn];
;         u32x4 o; o[0] = pk_bf16(v[0], v[1]); o[1] = pk_bf16(v[2], v[3]); o[2] = pk_bf16(v[4], v[5]); o[3] = pk_bf16(v[6], v[7]);
;         *(u32x4*)(dst + (size_t)(n0 + nn) * dst_ld + dst_koff + k0 + ks) = o;
;     }
;     __syncthreads();
; DI void phase_convert_weights(unsigned char* ws, int l, unsigned char* lds, int t_lo, int t_hi, int bid_off) {
;     ...
;         } else if (it < T2c) { const int j = it - T2b, nt = j / 4, kt = j % 4;
;             tr_tile(PIN(19), 1024, kt * 64, nt * 64, 3, (bf16_t*)(ws + WS_WBR) + 2048 * 512, 512, 0, tile);
.LBB0_529:
	s_andn2_b64 vcc, exec, s[20:21]
	s_cbranch_vccnz .LBB0_531
	v_mov_b32_e32 v0, v176
	s_load_dwordx2 s[20:21], s[0:1], 0x98
	s_waitcnt lgkmcnt(0)
	s_lshl_b32 s20, s3, 4
	v_ashrrev_i32_e32 v2, 4, v0
	v_lshlrev_b32_e32 v3, 4, v0
	v_and_b32_e32 v3, 0xf0, v3
	v_mul_lo_u32 v2, v2, s81
	v_add3_u32 v2, 0, v3, v2
	v_ashrrev_i32_e32 v8, 3, v0
	v_lshlrev_b32_e32 v0, 3, v0
	ds_write2_b32 v2, v1, v1 offset1:1
	ds_write2_b32 v2, v1, v1 offset0:2 offset1:3
	v_add_u32_e32 v3, 0x2080, v2
	v_add_u32_e32 v2, 0x2088, v2
	v_and_b32_e32 v0, 56, v0
	ds_write2_b32 v3, v1, v1 offset1:1
	ds_write2_b32 v2, v1, v1 offset1:1
	v_lshlrev_b32_e32 v2, 2, v8
	v_mul_u32_u24_e32 v3, 0x104, v0
	v_add3_u32 v6, 0, v2, v3
	s_and_b32 s20, s20, 0x7fc0
	s_waitcnt vmcnt(0) lgkmcnt(0)
	s_barrier
	ds_read2_b32 v[2:3], v6 offset1:65
	ds_read2_b32 v[4:5], v6 offset0:130 offset1:195
	v_add_u32_e32 v6, 0x400, v6
	s_addk_i32 s20, 0xa000
	s_waitcnt lgkmcnt(1)
	v_cvt_pk_bf16_f32 v2, v2, v3
	s_waitcnt lgkmcnt(0)
	v_cvt_pk_bf16_f32 v3, v4, v5
	ds_read2_b32 v[4:5], v6 offset0:4 offset1:69
	ds_read2_b32 v[6:7], v6 offset0:134 offset1:199
	s_waitcnt lgkmcnt(1)
	v_cvt_pk_bf16_f32 v4, v4, v5
	s_waitcnt lgkmcnt(0)
	v_cvt_pk_bf16_f32 v5, v6, v7
	v_add_u32_e32 v6, s20, v8
	v_ashrrev_i32_e32 v7, 31, v6
	v_lshlrev_b64 v[6:7], 10, v[6:7]
	s_lshl_b32 s20, s3, 7
	v_lshl_add_u64 v[6:7], s[14:15], 0, v[6:7]
	s_and_b32 s72, s20, 0x180
	v_lshl_add_u64 v[6:7], v[6:7], 0, s[72:73]
	v_lshlrev_b32_e32 v0, 1, v0
	v_lshl_add_u64 v[6:7], v[6:7], 0, v[0:1]
	global_store_dwordx4 v[6:7], v[2:5], off
	s_waitcnt lgkmcnt(0)
	s_barrier

; #define PIN(i) (((KargTbl)__builtin_amdgcn_kernarg_segment_ptr())[i])
; DI unsigned pk_bf16(float lo, float hi) { unsigned r; asm("v_cvt_pk_bf16_f32 %0, %1, %2" : "=v"(r) : "v"(lo), "v"(hi)); return r; }
; DI int otid() { int t = threadIdx.x; asm volatile("" : "+v"(t)); return t; }
; DI void tr_tile(const float* src, int src_ld, int k0, int n0, int mode, bf16_t* dst, int dst_ld, int dst_koff, float* tile) {
;     const int tid = otid();
;     {   const int nn4 = (tid & 15) * 4; const int np = n0 + nn4;
;         int col = np; bool valid = true;
;         if (mode == 1) valid = np < IN_DIM;
;         if (mode == 3) valid = false;
;         if (mode == 2) { const int pn = np >> 8, bj = (np >> 7) & 1, jj = np & 127; col = bj * DFF + pn * 128 + jj; }
; #pragma unroll
;         for (int i = 0; i < 2; ++i) { const int kk = (tid >> 4) + 32 * i;
;             f32x4 v = (f32x4){0.f, 0.f, 0.f, 0.f};
;             if (valid) v = __builtin_nontemporal_load((const f32x4*)(src + (size_t)(k0 + kk) * src_ld + col));
;             tile[kk * 65 + nn4] = v[0]; tile[kk * 65 + nn4 + 1] = v[1]; tile[kk * 65 + nn4 + 2] = v[2]; tile[kk * 65 + nn4 + 3] = v[3]; }
;     }
;     __syncthreads();
;     {   const int nn = tid >> 3, ks = (tid & 7) * 8;
;         float v[8];
; #pragma unroll
;         for (int j = 0; j < 8; ++j) v[j] = tile[(ks + j) * 65 + nn];
;         u32x4 o; o[0] = pk_bf16(v[0], v[1]); o[1] = pk_bf16(v[2], v[3]); o[2] = pk_bf16(v[4], v[5]); o[3] = pk_bf16(v[6], v[7]);
;         *(u32x4*)(dst + (size_t)(n0 + nn) * dst_ld + dst_koff + k0 + ks) = o;
;     }
;     __syncthreads();
; DI void phase_convert_weights(unsigned char* ws, int l, unsigned char* lds, int t_lo, int t_hi, int bid_off) {
;     ...
;         } else if (it < T2) { const int j = it - T1, nt = j / 4, kt = j % 4;
;             tr_tile(PIN(18) + (size_t)l * 256 * 1024, 1024, kt * 64, nt * 64, 0, (bf16_t*)(ws + WS_WBR) + 1024 * 512, 512, 0, tile);
.LBB0_535:
	s_andn2_b64 vcc, exec, s[20:21]
	s_cbranch_vccnz .LBB0_537
	s_load_dwordx2 s[20:21], s[0:1], 0x90
	v_mov_b32_e32 v10, v176
	s_waitcnt lgkmcnt(0)
	s_add_u32 s44, s20, s12
	s_addc_u32 s45, s21, s13
	s_lshl_b32 s20, s3, 6
	s_lshl_b32 s21, s3, 4
	s_and_b32 s20, s20, 0xc0
	s_and_b32 s21, s21, 0x7fc0
	v_lshlrev_b32_e32 v0, 2, v10
	v_ashrrev_i32_e32 v11, 4, v10
	s_addk_i32 s21, 0xa800
	v_and_b32_e32 v2, 60, v0
	v_add_u32_e32 v8, s20, v11
	v_or_b32_e32 v0, s21, v2
	v_ashrrev_i32_e32 v9, 31, v8
	v_lshlrev_b32_e32 v12, 2, v2
	v_lshl_add_u64 v[6:7], v[0:1], 2, s[44:45]
	v_lshlrev_b64 v[2:3], 12, v[8:9]
	v_lshl_add_u64 v[2:3], v[6:7], 0, v[2:3]
	global_load_dwordx4 v[2:5], v[2:3], off nt
	v_mul_lo_u32 v0, v11, s81
	v_add3_u32 v0, 0, v12, v0
	s_lshl_b32 s72, s20, 1
	v_add_u32_e32 v104, 32, v8
	v_ashrrev_i32_e32 v105, 31, v104
	v_lshlrev_b64 v[104:105], 12, v[104:105]
	v_lshl_add_u64 v[104:105], v[6:7], 0, v[104:105]
	global_load_dwordx4 v[100:103], v[104:105], off nt
	s_waitcnt vmcnt(0)
	ds_write2_b32 v0, v2, v3 offset1:1
	ds_write2_b32 v0, v4, v5 offset0:2 offset1:3
	v_add_u32_e32 v6, 0x2080, v0
	v_add_u32_e32 v0, 0x2088, v0
	ds_write2_b32 v6, v100, v101 offset1:1
	v_lshlrev_b32_e32 v2, 3, v10
	ds_write2_b32 v0, v102, v103 offset1:1
	v_ashrrev_i32_e32 v0, 3, v10
	v_and_b32_e32 v8, 56, v2
	v_lshlrev_b32_e32 v2, 2, v0
	v_mul_u32_u24_e32 v3, 0x104, v8
	v_add3_u32 v6, 0, v2, v3
	s_waitcnt lgkmcnt(0)
	s_barrier
	ds_read2_b32 v[2:3], v6 offset1:65
	ds_read2_b32 v[4:5], v6 offset0:130 offset1:195
	v_add_u32_e32 v6, 0x400, v6
	s_waitcnt lgkmcnt(1)
	v_cvt_pk_bf16_f32 v2, v2, v3
	s_waitcnt lgkmcnt(0)
	v_cvt_pk_bf16_f32 v3, v4, v5
	ds_read2_b32 v[4:5], v6 offset0:4 offset1:69
	ds_read2_b32 v[6:7], v6 offset0:134 offset1:199
	s_waitcnt lgkmcnt(1)
	v_cvt_pk_bf16_f32 v4, v4, v5
	s_waitcnt lgkmcnt(0)
	v_cvt_pk_bf16_f32 v5, v6, v7
	v_add_u32_e32 v6, s21, v0
	v_ashrrev_i32_e32 v7, 31, v6
	v_lshlrev_b64 v[6:7], 10, v[6:7]
	v_lshl_add_u64 v[6:7], s[16:17], 0, v[6:7]
	v_lshl_add_u64 v[6:7], v[6:7], 0, s[72:73]
	v_lshlrev_b32_e32 v0, 1, v8
	v_lshl_add_u64 v[6:7], v[6:7], 0, v[0:1]
	global_store_dwordx4 v[6:7], v[2:5], off
	s_waitcnt lgkmcnt(0)
	s_barrier

; #define PIN(i) (((KargTbl)__builtin_amdgcn_kernarg_segment_ptr())[i])
; DI unsigned pk_bf16(float lo, float hi) { unsigned r; asm("v_cvt_pk_bf16_f32 %0, %1, %2" : "=v"(r) : "v"(lo), "v"(hi)); return r; }
; DI int otid() { int t = threadIdx.x; asm volatile("" : "+v"(t)); return t; }
; DI void tr_tile(const float* src, int src_ld, int k0, int n0, int mode, bf16_t* dst, int dst_ld, int dst_koff, float* tile) {
;     const int tid = otid();
;     {   const int nn4 = (tid & 15) * 4; const int np = n0 + nn4;
;         int col = np; bool valid = true;
;         if (mode == 1) valid = np < IN_DIM;
;         if (mode == 3) valid = false;
;         if (mode == 2) { const int pn = np >> 8, bj = (np >> 7) & 1, jj = np & 127; col = bj * DFF + pn * 128 + jj; }
; #pragma unroll
;         for (int i = 0; i < 2; ++i) { const int kk = (tid >> 4) + 32 * i;
;             f32x4 v = (f32x4){0.f, 0.f, 0.f, 0.f};
;             if (valid) v = __builtin_nontemporal_load((const f32x4*)(src + (size_t)(k0 + kk) * src_ld + col));
;             tile[kk * 65 + nn4] = v[0]; tile[kk * 65 + nn4 + 1] = v[1]; tile[kk * 65 + nn4 + 2] = v[2]; tile[kk * 65 + nn4 + 3] = v[3]; }
;     }
;     __syncthreads();
;     {   const int nn = tid >> 3, ks = (tid & 7) * 8;
;         float v[8];
; #pragma unroll
;         for (int j = 0; j < 8; ++j) v[j] = tile[(ks + j) * 65 + nn];
;         u32x4 o; o[0] = pk_bf16(v[0], v[1]); o[1] = pk_bf16(v[2], v[3]); o[2] = pk_bf16(v[4], v[5]); o[3] = pk_bf16(v[6], v[7]);
;         *(u32x4*)(dst + (size_t)(n0 + nn) * dst_ld + dst_koff + k0 + ks) = o;
;     }
;     __syncthreads();
; DI void phase_convert_weights(unsigned char* ws, int l, unsigned char* lds, int t_lo, int t_hi, int bid_off) {
;     ...
;         } else if (it < T1) { const int j = it - T0, nt = j / 8, kt = j % 8;
;             tr_tile(PIN(17) + (size_t)l * 512 * 1024, 1024, kt * 64, nt * 64, 0, (bf16_t*)(ws + WS_WBR), 512, 0, tile);
.LBB0_538:
	s_andn2_b64 vcc, exec, s[20:21]
	s_cbranch_vccnz .LBB0_540
	s_load_dwordx2 s[20:21], s[0:1], 0x88
	v_mov_b32_e32 v10, v176
	s_waitcnt lgkmcnt(0)
	s_add_u32 s44, s20, s18
	s_addc_u32 s45, s21, s19
	s_lshl_b32 s20, s3, 6
	s_lshl_b32 s21, s3, 3
	s_and_b32 s20, s20, 0x1c0
	s_and_b32 s21, s21, 0x3fc0
	v_lshlrev_b32_e32 v0, 2, v10
	v_ashrrev_i32_e32 v11, 4, v10
	s_addk_i32 s21, 0xd800
	v_and_b32_e32 v2, 60, v0
	v_add_u32_e32 v8, s20, v11
	v_or_b32_e32 v0, s21, v2
	v_ashrrev_i32_e32 v9, 31, v8
	v_lshlrev_b32_e32 v12, 2, v2
	v_lshl_add_u64 v[6:7], v[0:1], 2, s[44:45]
	v_lshlrev_b64 v[2:3], 12, v[8:9]
	v_lshl_add_u64 v[2:3], v[6:7], 0, v[2:3]
	global_load_dwordx4 v[2:5], v[2:3], off nt
	v_mul_lo_u32 v0, v11, s81
	v_add3_u32 v0, 0, v12, v0
	s_lshl_b32 s72, s20, 1
	v_add_u32_e32 v104, 32, v8
	v_ashrrev_i32_e32 v105, 31, v104
	v_lshlrev_b64 v[104:105], 12, v[104:105]
	v_lshl_add_u64 v[104:105], v[6:7], 0, v[104:105]
	global_load_dwordx4 v[100:103], v[104:105], off nt
	s_waitcnt vmcnt(0)
	ds_write2_b32 v0, v2, v3 offset1:1
	ds_write2_b32 v0, v4, v5 offset0:2 offset1:3
	v_add_u32_e32 v6, 0x2080, v0
	v_add_u32_e32 v0, 0x2088, v0
	ds_write2_b32 v6, v100, v101 offset1:1
	v_lshlrev_b32_e32 v2, 3, v10
	ds_write2_b32 v0, v102, v103 offset1:1
	v_ashrrev_i32_e32 v0, 3, v10
	v_and_b32_e32 v8, 56, v2
	v_lshlrev_b32_e32 v2, 2, v0
	v_mul_u32_u24_e32 v3, 0x104, v8
	v_add3_u32 v6, 0, v2, v3
	s_waitcnt lgkmcnt(0)
	s_barrier
	ds_read2_b32 v[2:3], v6 offset1:65
	ds_read2_b32 v[4:5], v6 offset0:130 offset1:195
	v_add_u32_e32 v6, 0x400, v6
	s_waitcnt lgkmcnt(1)
	v_cvt_pk_bf16_f32 v2, v2, v3
	s_waitcnt lgkmcnt(0)
	v_cvt_pk_bf16_f32 v3, v4, v5
	ds_read2_b32 v[4:5], v6 offset0:4 offset1:69
	ds_read2_b32 v[6:7], v6 offset0:134 offset1:199
	s_waitcnt lgkmcnt(1)
	v_cvt_pk_bf16_f32 v4, v4, v5
	s_waitcnt lgkmcnt(0)
	v_cvt_pk_bf16_f32 v5, v6, v7
	v_add_u32_e32 v6, s21, v0
	v_ashrrev_i32_e32 v7, 31, v6
	v_lshlrev_b64 v[6:7], 10, v[6:7]
	v_lshl_add_u64 v[6:7], s[40:41], 0, v[6:7]
	v_lshl_add_u64 v[6:7], v[6:7], 0, s[72:73]
	v_lshlrev_b32_e32 v0, 1, v8
	v_lshl_add_u64 v[6:7], v[6:7], 0, v[0:1]
	global_store_dwordx4 v[6:7], v[2:5], off
	s_waitcnt lgkmcnt(0)
	s_barrier
